# phase-1 tile top: dropped the loop-header vmcnt(0) that only drained the previous tile's stores
# baseline (speedup 1.0000x reference)
; DI void load_rstd(float (&rs)[4], const float* ssq, int row0, int lr) {
; #pragma unroll
;   for (int mt = 0; mt < 4; ++mt) {
;     const float4* q = (const float4*)(ssq + (size_t)(row0 + mt * 16 + lr) * 16);
;     const float4 a = q[0], b = q[1], c = q[2], d = q[3];
;     const float s = ((a.x + a.y) + (a.z + a.w)) + ((b.x + b.y) + (b.z + b.w)) + ((c.x + c.y) + (c.z + c.w)) + ((d.x + d.y) + (d.z + d.w));
;     rs[mt] = rsqrtf(s * (1.0f / 1024.0f) + EPS);
;   }
; }
.LBB0_637:
	s_ashr_i32 s1, s28, 9
	s_lshr_b32 s2, s1, 29
	s_add_i32 s2, s1, s2
	s_lshl_b32 s2, s2, 3
	s_and_b32 s4, s2, 0xffffffc0
	s_and_b32 s2, s26, 56
	s_bfe_u32 s5, s28, 0x30003
	s_or_b32 s2, s2, s5
	s_lshl_b32 s1, s1, 3
	s_or_b32 s2, s2, s4
	s_sub_i32 s1, s1, s4
	s_bfe_u32 s4, s28, 0x30006
	s_or_b32 s1, s1, s4
	s_cmpk_lt_i32 s2, 0x80
	s_cselect_b64 s[4:5], -1, 0
	s_cmp_lt_i32 s1, 63
	s_cselect_b64 s[16:17], -1, 0
	s_and_b64 s[4:5], s[4:5], s[16:17]
	s_andn2_b64 vcc, exec, s[4:5]
	s_cbranch_vccnz .LBB0_636
	s_lshl_b32 s18, s2, 7
	v_add_u32_e32 v99, s18, v101
	v_or_b32_e32 v70, v99, v97
	v_ashrrev_i32_e32 v71, 31, v70
	v_readlane_b32 s20, v253, 13
	v_lshlrev_b64 v[0:1], 6, v[70:71]
	v_readlane_b32 s21, v253, 14
	v_or_b32_e32 v68, 16, v70
	v_ashrrev_i32_e32 v69, 31, v68
	v_lshl_add_u64 v[12:13], s[20:21], 0, v[0:1]
	global_load_dwordx4 v[0:3], v[12:13], off offset:48
	global_load_dwordx4 v[4:7], v[12:13], off offset:32
	global_load_dwordx4 v[8:11], v[12:13], off offset:16
	s_nop 0
	global_load_dwordx4 v[12:15], v[12:13], off
	s_mov_b32 s2, 0x358637bd
	s_mov_b32 s22, 0x3a800000
	v_or_b32_e32 v66, 32, v70
	v_ashrrev_i32_e32 v67, 31, v66
	v_or_b32_e32 v64, 48, v70
	v_ashrrev_i32_e32 v65, 31, v64
	s_ashr_i32 s19, s18, 31
	s_lshl_b32 s16, s1, 7
	v_or_b32_e32 v94, s16, v85
	s_waitcnt vmcnt(1)
	v_mov_b32_e32 v18, v9
	s_waitcnt vmcnt(0)
	v_mov_b32_e32 v16, v13
	v_mov_b32_e32 v17, v14
	v_mov_b32_e32 v19, v10
	v_mov_b32_e32 v13, v15
	v_mov_b32_e32 v9, v11
	v_pk_add_f32 v[12:13], v[16:17], v[12:13]
	v_pk_add_f32 v[8:9], v[18:19], v[8:9]
	v_pk_add_f32 v[10:11], v[12:13], v[12:13] op_sel:[0,1] op_sel_hi:[1,0]
	v_pk_add_f32 v[8:9], v[8:9], v[8:9] op_sel:[0,1] op_sel_hi:[1,0]
	v_mov_b32_e32 v11, v0
	v_mov_b32_e32 v9, v1
	v_pk_add_f32 v[0:1], v[10:11], v[8:9]
	v_mov_b32_e32 v8, v5
	v_pk_add_f32 v[4:5], v[4:5], v[8:9]
	s_nop 0
	v_mov_b32_e32 v5, v2
	v_mov_b32_e32 v2, v7
	v_pk_add_f32 v[6:7], v[6:7], v[2:3]
	s_nop 0
	v_mov_b32_e32 v7, v3
	v_pk_add_f32 v[2:3], v[4:5], v[6:7]
	s_nop 0
	v_pk_add_f32 v[16:17], v[0:1], v[2:3]
	v_lshlrev_b64 v[0:1], 6, v[68:69]
	v_lshl_add_u64 v[12:13], s[20:21], 0, v[0:1]
	global_load_dwordx4 v[0:3], v[12:13], off offset:48
	global_load_dwordx4 v[4:7], v[12:13], off offset:32
	global_load_dwordx4 v[8:11], v[12:13], off offset:16
	s_nop 0
	global_load_dwordx4 v[12:15], v[12:13], off
	s_waitcnt vmcnt(1)
	v_mov_b32_e32 v20, v9
	s_waitcnt vmcnt(0)
	v_mov_b32_e32 v18, v13
	v_mov_b32_e32 v19, v14
	v_mov_b32_e32 v21, v10
	v_mov_b32_e32 v13, v15
	v_mov_b32_e32 v9, v11
	v_pk_add_f32 v[12:13], v[18:19], v[12:13]
	v_pk_add_f32 v[8:9], v[20:21], v[8:9]
	v_pk_add_f32 v[10:11], v[12:13], v[12:13] op_sel:[0,1] op_sel_hi:[1,0]
	v_pk_add_f32 v[8:9], v[8:9], v[8:9] op_sel:[0,1] op_sel_hi:[1,0]
	v_mov_b32_e32 v11, v0
	v_mov_b32_e32 v9, v1
	v_pk_add_f32 v[0:1], v[10:11], v[8:9]
	v_mov_b32_e32 v8, v5
	v_pk_add_f32 v[4:5], v[4:5], v[8:9]
	s_nop 0
	v_mov_b32_e32 v5, v2
	v_mov_b32_e32 v2, v7
	v_pk_add_f32 v[6:7], v[6:7], v[2:3]
	s_nop 0
	v_mov_b32_e32 v7, v3
	v_pk_add_f32 v[2:3], v[4:5], v[6:7]
	s_nop 0
	v_pk_add_f32 v[0:1], v[0:1], v[2:3]
	v_mov_b32_e32 v3, v16
	v_mov_b32_e32 v2, v0
	v_mov_b32_e32 v16, v1
	v_pk_add_f32 v[0:1], v[2:3], v[16:17]
	v_mov_b64_e32 v[16:17], s[2:3]
	v_pk_fma_f32 v[0:1], v[0:1], s[22:23], v[16:17] op_sel_hi:[1,0,0]
	s_mov_b32 s2, 0x800000
	v_mul_f32_e32 v2, 0x4b800000, v1
	v_cmp_gt_f32_e64 s[4:5], s2, v1
	v_cmp_gt_f32_e32 vcc, s2, v0
	s_nop 0
	v_cndmask_b32_e64 v1, v1, v2, s[4:5]
	v_rsq_f32_e32 v1, v1
	s_nop 0
	v_mul_f32_e32 v2, 0x45800000, v1
	v_cndmask_b32_e64 v98, v1, v2, s[4:5]
	v_mul_f32_e32 v1, 0x4b800000, v0
	v_cndmask_b32_e32 v0, v0, v1, vcc
	v_rsq_f32_e32 v0, v0
	s_nop 0
	v_mul_f32_e32 v1, 0x45800000, v0
	v_cndmask_b32_e32 v96, v0, v1, vcc
	v_lshlrev_b64 v[0:1], 6, v[66:67]
	v_lshl_add_u64 v[12:13], s[20:21], 0, v[0:1]
	global_load_dwordx4 v[0:3], v[12:13], off offset:48
	global_load_dwordx4 v[4:7], v[12:13], off offset:32
	global_load_dwordx4 v[8:11], v[12:13], off offset:16
	s_nop 0
	global_load_dwordx4 v[12:15], v[12:13], off
	s_waitcnt vmcnt(1)
	v_mov_b32_e32 v20, v9
	s_waitcnt vmcnt(0)
	v_mov_b32_e32 v18, v13
	v_mov_b32_e32 v19, v14
	v_mov_b32_e32 v21, v10
	v_mov_b32_e32 v13, v15
	v_mov_b32_e32 v9, v11
	v_pk_add_f32 v[12:13], v[18:19], v[12:13]
	v_pk_add_f32 v[8:9], v[20:21], v[8:9]
	v_pk_add_f32 v[10:11], v[12:13], v[12:13] op_sel:[0,1] op_sel_hi:[1,0]
	v_pk_add_f32 v[8:9], v[8:9], v[8:9] op_sel:[0,1] op_sel_hi:[1,0]
	v_mov_b32_e32 v11, v0
	v_mov_b32_e32 v9, v1
	v_pk_add_f32 v[0:1], v[10:11], v[8:9]
	v_mov_b32_e32 v8, v5
	v_pk_add_f32 v[4:5], v[4:5], v[8:9]
	s_nop 0
	v_mov_b32_e32 v5, v2
	v_mov_b32_e32 v2, v7
	v_pk_add_f32 v[6:7], v[6:7], v[2:3]
	s_nop 0
	v_mov_b32_e32 v7, v3
	v_pk_add_f32 v[2:3], v[4:5], v[6:7]
	s_nop 0
	v_pk_add_f32 v[18:19], v[0:1], v[2:3]
	v_lshlrev_b64 v[0:1], 6, v[64:65]
	v_lshl_add_u64 v[12:13], s[20:21], 0, v[0:1]
	global_load_dwordx4 v[0:3], v[12:13], off offset:48
	global_load_dwordx4 v[4:7], v[12:13], off offset:32
	global_load_dwordx4 v[8:11], v[12:13], off offset:16
	s_nop 0
	global_load_dwordx4 v[12:15], v[12:13], off
	s_waitcnt vmcnt(1)
	v_mov_b32_e32 v22, v9
	s_waitcnt vmcnt(0)
	v_mov_b32_e32 v20, v13
	v_mov_b32_e32 v21, v14
	v_mov_b32_e32 v23, v10
	v_mov_b32_e32 v13, v15
	v_mov_b32_e32 v9, v11
	v_pk_add_f32 v[12:13], v[20:21], v[12:13]
	v_pk_add_f32 v[8:9], v[22:23], v[8:9]
	v_pk_add_f32 v[10:11], v[12:13], v[12:13] op_sel:[0,1] op_sel_hi:[1,0]
	v_pk_add_f32 v[8:9], v[8:9], v[8:9] op_sel:[0,1] op_sel_hi:[1,0]
	v_mov_b32_e32 v11, v0
	v_mov_b32_e32 v9, v1
	v_pk_add_f32 v[0:1], v[10:11], v[8:9]
	v_mov_b32_e32 v8, v5
	v_pk_add_f32 v[4:5], v[4:5], v[8:9]
	s_nop 0
	v_mov_b32_e32 v5, v2
	v_mov_b32_e32 v2, v7
	v_pk_add_f32 v[6:7], v[6:7], v[2:3]
	s_nop 0
	v_mov_b32_e32 v7, v3
	v_pk_add_f32 v[2:3], v[4:5], v[6:7]
	s_nop 0
	v_pk_add_f32 v[0:1], v[0:1], v[2:3]
	v_mov_b32_e32 v3, v18
	v_mov_b32_e32 v2, v0
	v_mov_b32_e32 v18, v1
	v_pk_add_f32 v[0:1], v[2:3], v[18:19]
	s_nop 0
	v_pk_fma_f32 v[0:1], v[0:1], s[22:23], v[16:17] op_sel_hi:[1,0,0]
	s_nop 0
	v_mul_f32_e32 v2, 0x4b800000, v1
	v_cmp_gt_f32_e64 s[4:5], s2, v1
	v_cmp_gt_f32_e32 vcc, s2, v0
	s_nop 0
	v_cndmask_b32_e64 v1, v1, v2, s[4:5]
	v_rsq_f32_e32 v1, v1
	s_nop 0
	v_mul_f32_e32 v2, 0x45800000, v1
	v_cndmask_b32_e64 v102, v1, v2, s[4:5]
	v_mul_f32_e32 v1, 0x4b800000, v0
	v_cndmask_b32_e32 v0, v0, v1, vcc
	v_rsq_f32_e32 v0, v0
	s_lshl_b64 s[4:5], s[18:19], 11
	v_readlane_b32 s18, v253, 11
	v_readlane_b32 s19, v253, 12
	s_add_u32 s18, s18, s4
	v_mul_f32_e32 v1, 0x45800000, v0
	s_addc_u32 s19, s19, s5
	v_cndmask_b32_e32 v100, v0, v1, vcc
	s_cmp_lt_i32 s1, 51
	s_mov_b64 s[4:5], -1
	s_cbranch_scc0 .LBB0_691
; #define GL_LOAD(s_, kt_) if (VAR != 1) { a##s_##0 = GL_A(0, kt_); a##s_##1 = GL_A(1, kt_); a##s_##2 = GL_A(2, kt_); a##s_##3 = GL_A(3, kt_); b##s_##0 = GL_B(0, kt_); b##s_##1 = GL_B(1, kt_); b##s_##2 = GL_B(2, kt_); b##s_##3 = GL_B(3, kt_); }
; #define LDS_STORE(s_, buf_) if (VAR != 2) { LDS_ST1(sA, 0, buf_, a##s_##0) LDS_ST1(sA, 1, buf_, a##s_##1) LDS_ST1(sA, 2, buf_, a##s_##2) LDS_ST1(sA, 3, buf_, a##s_##3) LDS_ST1(sB, 0, buf_, b##s_##0) LDS_ST1(sB, 1, buf_, b##s_##1) LDS_ST1(sB, 2, buf_, b##s_##2) LDS_ST1(sB, 3, buf_, b##s_##3) }
;     ...
;   uint4 a00 = {}, a01 = {}, a02 = {}, a03 = {}, b00 = {}, b01 = {}, b02 = {}, b03 = {}, a10 = {}, a11 = {}, a12 = {}, a13 = {}, b10 = {}, b11 = {}, b12 = {}, b13 = {};
;   constexpr int nk = NK;
;   const int sw0 = (g ^ ((lr >> 1) & 7)) << 4, sw1 = sw0 ^ 64;
;   const int r0 = tid >> 3, kc = tid & 7, kcs = kc ^ ((r0 >> 1) & 7);
;     ...
;   GL_LOAD(0, 0)
;   GL_LOAD(1, 1)
;   LDS_STORE(0, 0)
;   if (VAR != 4) __syncthreads();
; #pragma unroll
;   for (int kt = 0; kt < nk; kt += 2) {
;     if (kt + 2 < nk) { GL_LOAD(0, kt + 2) }
;     MMA_TILE(0)
;     LDS_STORE(1, 1)
;     if (VAR != 4) __syncthreads();
	v_mov_b32_e32 v56, v148
	s_ashr_i32 s17, s16, 31
	s_lshl_b64 s[4:5], s[16:17], 11
	v_ashrrev_i32_e32 v16, 3, v56
	v_readlane_b32 s1, v252, 19
	v_ashrrev_i32_e32 v17, 31, v16
	s_add_u32 s4, s1, s4
	v_readlane_b32 s1, v252, 20
	v_lshlrev_b64 v[8:9], 11, v[16:17]
	v_lshlrev_b32_e32 v17, 4, v56
	v_add_u32_e32 v18, 32, v16
	s_addc_u32 s5, s1, s5
	v_lshl_add_u64 v[0:1], s[18:19], 0, v[8:9]
	v_and_b32_e32 v150, 0x70, v17
	v_ashrrev_i32_e32 v19, 31, v18
	v_add_u32_e32 v20, 64, v16
	v_lshl_add_u64 v[0:1], v[0:1], 0, v[150:151]
	v_lshlrev_b64 v[10:11], 11, v[18:19]
	v_ashrrev_i32_e32 v21, 31, v20
	v_add_u32_e32 v54, 0x60, v16
	v_lshl_add_u64 v[8:9], s[4:5], 0, v[8:9]
	global_load_dwordx4 v[22:25], v[0:1], off
	v_lshl_add_u64 v[2:3], s[18:19], 0, v[10:11]
	v_lshlrev_b64 v[12:13], 11, v[20:21]
	v_ashrrev_i32_e32 v55, 31, v54
	v_lshl_add_u64 v[8:9], v[8:9], 0, v[150:151]
	v_lshl_add_u64 v[2:3], v[2:3], 0, v[150:151]
	v_lshl_add_u64 v[4:5], s[18:19], 0, v[12:13]
	v_lshlrev_b64 v[14:15], 11, v[54:55]
	global_load_dwordx4 v[38:41], v[8:9], off
	global_load_dwordx4 v[26:29], v[2:3], off
	v_lshl_add_u64 v[4:5], v[4:5], 0, v[150:151]
	v_lshl_add_u64 v[6:7], s[18:19], 0, v[14:15]
	global_load_dwordx4 v[30:33], v[4:5], off
	v_lshl_add_u64 v[6:7], v[6:7], 0, v[150:151]
	v_lshl_add_u64 v[10:11], s[4:5], 0, v[10:11]
	global_load_dwordx4 v[34:37], v[6:7], off
	v_lshl_add_u64 v[10:11], v[10:11], 0, v[150:151]
	v_lshl_add_u64 v[12:13], s[4:5], 0, v[12:13]
	global_load_dwordx4 v[42:45], v[10:11], off
	v_lshl_add_u64 v[12:13], v[12:13], 0, v[150:151]
	v_lshl_add_u64 v[14:15], s[4:5], 0, v[14:15]
	global_load_dwordx4 v[46:49], v[12:13], off
	v_lshl_add_u64 v[14:15], v[14:15], 0, v[150:151]
	global_load_dwordx4 v[50:53], v[14:15], off
	v_lshlrev_b32_e32 v21, 3, v56
	v_and_b32_e32 v62, 48, v56
	s_movk_i32 s1, 0x70
	v_and_b32_e32 v19, 15, v56
	v_lshrrev_b32_e32 v55, 1, v56
	v_lshlrev_b32_e32 v57, 7, v56
	v_and_b32_e32 v63, 0x70, v21
	v_bitop3_b32 v95, v21, v62, s1 bitop3:0x6c
	v_bitop3_b32 v21, v17, s1, v56 bitop3:0x48
	v_and_or_b32 v103, v55, s29, v19
	v_and_b32_e32 v150, 0x2780, v57
	v_lshl_or_b32 v19, v20, 7, v21
	v_lshl_or_b32 v20, v54, 7, v21
	global_load_dwordx4 v[54:57], v[0:1], off offset:128
	global_load_dwordx4 v[58:61], v[8:9], off offset:128
	global_load_dwordx4 v[72:75], v[2:3], off offset:128
	global_load_dwordx4 v[76:79], v[4:5], off offset:128
	global_load_dwordx4 v[80:83], v[6:7], off offset:128
	global_load_dwordx4 v[104:107], v[10:11], off offset:128
	global_load_dwordx4 v[108:111], v[12:13], off offset:128
	global_load_dwordx4 v[112:115], v[14:15], off offset:128
	v_lshl_or_b32 v17, v16, 7, v21
	v_or_b32_e32 v16, v150, v95
	v_lshlrev_b32_e32 v103, 7, v103
	v_lshl_or_b32 v18, v18, 7, v21
	v_bitop3_b32 v21, v103, v63, v62 bitop3:0xf6
	s_movk_i32 s1, 0x1ff
	v_cmp_lt_i32_e32 vcc, s1, v94
	s_mov_b64 s[22:23], -1
	s_mov_b64 s[20:21], 0
	s_waitcnt vmcnt(15)
	ds_write_b128 v17, v[22:25]
	s_waitcnt vmcnt(14)
	ds_write_b128 v17, v[38:41] offset:32768
	s_waitcnt vmcnt(13)
	ds_write_b128 v18, v[26:29]
	s_waitcnt vmcnt(12)
	ds_write_b128 v19, v[30:33]
	s_waitcnt vmcnt(11)
	ds_write_b128 v20, v[34:37]
	s_waitcnt vmcnt(10)
	ds_write_b128 v18, v[42:45] offset:32768
	s_waitcnt vmcnt(9)
	ds_write_b128 v19, v[46:49] offset:32768
	s_waitcnt vmcnt(8)
	ds_write_b128 v20, v[50:53] offset:32768
	s_waitcnt lgkmcnt(0)
	s_barrier
	s_setprio 1
	ds_read_b128 v[22:25], v16 offset:32768
	ds_read_b128 v[30:33], v21
	s_waitcnt lgkmcnt(0)
	v_mfma_f32_16x16x32_f16 v[38:41], v[22:25], v[30:33], 0
	ds_read_b128 v[26:29], v16 offset:34816
	s_waitcnt lgkmcnt(0)
	v_mfma_f32_16x16x32_f16 v[46:49], v[26:29], v[30:33], 0
	ds_read_b128 v[34:37], v21 offset:2048
	ds_read_b128 v[42:45], v16 offset:36864
	s_waitcnt lgkmcnt(0)
	v_mfma_f32_16x16x32_f16 v[116:119], v[42:45], v[30:33], 0
	ds_read_b128 v[50:53], v16 offset:38912
	s_waitcnt lgkmcnt(0)
	v_mfma_f32_16x16x32_f16 v[120:123], v[50:53], v[30:33], 0
	ds_read_b128 v[30:33], v21 offset:4096
	v_mfma_f32_16x16x32_f16 v[124:127], v[22:25], v[34:37], 0
	ds_read_b128 v[136:139], v21 offset:6144
	s_waitcnt lgkmcnt(0)
	v_mfma_f32_16x16x32_f16 v[162:165], v[22:25], v[136:139], 0
	s_waitcnt vmcnt(7)
	ds_write_b128 v17, v[54:57] offset:16384
	v_mfma_f32_16x16x32_f16 v[128:131], v[26:29], v[34:37], 0
	s_waitcnt vmcnt(5)
	ds_write_b128 v18, v[72:75] offset:16384
	v_mfma_f32_16x16x32_f16 v[132:135], v[42:45], v[34:37], 0
	s_waitcnt vmcnt(4)
	ds_write_b128 v19, v[76:79] offset:16384
	v_mfma_f32_16x16x32_f16 v[34:37], v[50:53], v[34:37], 0
	s_waitcnt vmcnt(3)
	ds_write_b128 v20, v[80:83] offset:16384
	v_mfma_f32_16x16x32_f16 v[140:143], v[22:25], v[30:33], 0
	v_xor_b32_e32 v22, 64, v95
	v_or_b32_e32 v22, v150, v22
	v_mfma_f32_16x16x32_f16 v[144:147], v[26:29], v[30:33], 0
	v_mfma_f32_16x16x32_f16 v[154:157], v[42:45], v[30:33], 0
	v_mfma_f32_16x16x32_f16 v[158:161], v[50:53], v[30:33], 0
	v_bitop3_b32 v32, v103, v95, 64 bitop3:0xf6
	ds_read_b128 v[166:169], v32
	ds_read_b128 v[192:195], v22 offset:36864
	s_waitcnt lgkmcnt(0)
	v_mfma_f32_16x16x32_f16 v[116:119], v[192:195], v[166:169], v[116:119]
	ds_read_b128 v[188:191], v32 offset:2048
	ds_read_b128 v[196:199], v22 offset:38912
	s_waitcnt lgkmcnt(0)
	v_mfma_f32_16x16x32_f16 v[120:123], v[196:199], v[166:169], v[120:123]
	ds_write_b128 v17, v[58:61] offset:49152
	v_mfma_f32_16x16x32_f16 v[132:135], v[192:195], v[188:191], v[132:135]
	s_waitcnt vmcnt(2)
	ds_write_b128 v18, v[104:107] offset:49152
	v_mfma_f32_16x16x32_f16 v[34:37], v[196:199], v[188:191], v[34:37]
	s_waitcnt vmcnt(1)
	ds_write_b128 v19, v[108:111] offset:49152
	s_waitcnt vmcnt(0)
; #define GL_LOAD(s_, kt_) if (VAR != 1) { a##s_##0 = GL_A(0, kt_); a##s_##1 = GL_A(1, kt_); a##s_##2 = GL_A(2, kt_); a##s_##3 = GL_A(3, kt_); b##s_##0 = GL_B(0, kt_); b##s_##1 = GL_B(1, kt_); b##s_##2 = GL_B(2, kt_); b##s_##3 = GL_B(3, kt_); }
; #define LDS_STORE(s_, buf_) if (VAR != 2) { LDS_ST1(sA, 0, buf_, a##s_##0) LDS_ST1(sA, 1, buf_, a##s_##1) LDS_ST1(sA, 2, buf_, a##s_##2) LDS_ST1(sA, 3, buf_, a##s_##3) LDS_ST1(sB, 0, buf_, b##s_##0) LDS_ST1(sB, 1, buf_, b##s_##1) LDS_ST1(sB, 2, buf_, b##s_##2) LDS_ST1(sB, 3, buf_, b##s_##3) }
;     ...
;   GL_LOAD(0, 0)
;   GL_LOAD(1, 1)
;   LDS_STORE(0, 0)
;   if (VAR != 4) __syncthreads();
; #pragma unroll
;   for (int kt = 0; kt < nk; kt += 2) {
;     if (kt + 2 < nk) { GL_LOAD(0, kt + 2) }
;     MMA_TILE(0)
;     LDS_STORE(1, 1)
;     if (VAR != 4) __syncthreads();
;     if (kt + 3 < nk) { GL_LOAD(1, kt + 3) }
;     MMA_TILE(1)
;     if (kt + 2 < nk) { LDS_STORE(0, 0) }
;     if (VAR != 4) __syncthreads();
	ds_write_b128 v20, v[112:115] offset:49152
	v_mfma_f32_16x16x32_f16 v[24:27], v[26:29], v[136:139], 0
	v_mfma_f32_16x16x32_f16 v[28:31], v[42:45], v[136:139], 0
	ds_read_b128 v[42:45], v22 offset:32768
	v_mfma_f32_16x16x32_f16 v[50:53], v[50:53], v[136:139], 0
	ds_read_b128 v[136:139], v22 offset:34816
	s_waitcnt lgkmcnt(1)
	v_mfma_f32_16x16x32_f16 v[38:41], v[42:45], v[166:169], v[38:41]
	v_mfma_f32_16x16x32_f16 v[124:127], v[42:45], v[188:191], v[124:127]
	s_waitcnt lgkmcnt(0)
	v_mfma_f32_16x16x32_f16 v[46:49], v[136:139], v[166:169], v[46:49]
	ds_read_b128 v[166:169], v32 offset:4096
	v_mfma_f32_16x16x32_f16 v[128:131], v[136:139], v[188:191], v[128:131]
	ds_read_b128 v[188:191], v32 offset:6144
	s_waitcnt lgkmcnt(1)
	v_mfma_f32_16x16x32_f16 v[140:143], v[42:45], v[166:169], v[140:143]
	s_waitcnt lgkmcnt(0)
	v_mfma_f32_16x16x32_f16 v[42:45], v[42:45], v[188:191], v[162:165]
	s_nop 2
	global_load_dwordx4 v[162:165], v[0:1], off offset:256
	v_mfma_f32_16x16x32_f16 v[144:147], v[136:139], v[166:169], v[144:147]
	v_mfma_f32_16x16x32_f16 v[24:27], v[136:139], v[188:191], v[24:27]
	v_mfma_f32_16x16x32_f16 v[154:157], v[192:195], v[166:169], v[154:157]
	v_mfma_f32_16x16x32_f16 v[158:161], v[196:199], v[166:169], v[158:161]
	global_load_dwordx4 v[166:169], v[2:3], off offset:256
	global_load_dwordx4 v[200:203], v[4:5], off offset:256
	global_load_dwordx4 v[204:207], v[6:7], off offset:256
	global_load_dwordx4 v[136:139], v[8:9], off offset:256
	global_load_dwordx4 v[208:211], v[10:11], off offset:256
	global_load_dwordx4 v[212:215], v[12:13], off offset:256
	global_load_dwordx4 v[220:223], v[14:15], off offset:256
	s_waitcnt lgkmcnt(0)
	s_barrier
	v_mfma_f32_16x16x32_f16 v[28:31], v[192:195], v[188:191], v[28:31]
	ds_read_b128 v[54:57], v16 offset:49152
	v_mfma_f32_16x16x32_f16 v[50:53], v[196:199], v[188:191], v[50:53]
	ds_read_b128 v[58:61], v16 offset:51200
	ds_read_b128 v[72:75], v21 offset:16384
	s_waitcnt lgkmcnt(0)
	v_mfma_f32_16x16x32_f16 v[38:41], v[54:57], v[72:75], v[38:41]
	ds_read_b128 v[76:79], v21 offset:18432
	s_waitcnt lgkmcnt(0)
	v_mfma_f32_16x16x32_f16 v[112:115], v[54:57], v[76:79], v[124:127]
	ds_read_b128 v[80:83], v16 offset:53248
	v_mfma_f32_16x16x32_f16 v[46:49], v[58:61], v[72:75], v[46:49]
	ds_read_b128 v[104:107], v16 offset:55296
	s_waitcnt lgkmcnt(1)
	v_mfma_f32_16x16x32_f16 v[108:111], v[80:83], v[72:75], v[116:119]
	v_mfma_f32_16x16x32_f16 v[116:119], v[58:61], v[76:79], v[128:131]
	ds_read_b128 v[124:127], v21 offset:22528
	s_waitcnt vmcnt(7)
	ds_write_b128 v17, v[162:165]
	s_waitcnt lgkmcnt(2)
	v_mfma_f32_16x16x32_f16 v[72:75], v[104:107], v[72:75], v[120:123]
	v_mfma_f32_16x16x32_f16 v[120:123], v[80:83], v[76:79], v[132:135]
	s_waitcnt vmcnt(6)
	ds_write_b128 v18, v[166:169]
	s_waitcnt vmcnt(5)
	ds_write_b128 v19, v[200:203]
	v_mfma_f32_16x16x32_f16 v[34:37], v[104:107], v[76:79], v[34:37]
	ds_read_b128 v[76:79], v21 offset:20480
	s_waitcnt lgkmcnt(0)
	v_mfma_f32_16x16x32_f16 v[128:131], v[54:57], v[76:79], v[140:143]
	s_waitcnt vmcnt(4)
	ds_write_b128 v20, v[204:207]
	v_mfma_f32_16x16x32_f16 v[42:45], v[54:57], v[124:127], v[42:45]
	ds_read_b128 v[54:57], v22 offset:49152
	v_mfma_f32_16x16x32_f16 v[132:135], v[58:61], v[76:79], v[144:147]
	s_nop 2
	ds_read_b128 v[144:147], v22 offset:55296
	v_mfma_f32_16x16x32_f16 v[24:27], v[58:61], v[124:127], v[24:27]
	ds_read_b128 v[58:61], v22 offset:51200
	v_mfma_f32_16x16x32_f16 v[140:143], v[80:83], v[76:79], v[154:157]
	s_waitcnt vmcnt(3)
	ds_write_b128 v17, v[136:139] offset:32768
	v_mfma_f32_16x16x32_f16 v[28:31], v[80:83], v[124:127], v[28:31]
	ds_read_b128 v[80:83], v32 offset:16384
	v_mfma_f32_16x16x32_f16 v[76:79], v[104:107], v[76:79], v[158:161]
	s_waitcnt vmcnt(2)
	ds_write_b128 v18, v[208:211] offset:32768
	v_mfma_f32_16x16x32_f16 v[50:53], v[104:107], v[124:127], v[50:53]
	ds_read_b128 v[104:107], v32 offset:18432
	s_waitcnt lgkmcnt(2)
	v_mfma_f32_16x16x32_f16 v[38:41], v[54:57], v[80:83], v[38:41]
	ds_read_b128 v[124:127], v22 offset:53248
	v_mfma_f32_16x16x32_f16 v[46:49], v[58:61], v[80:83], v[46:49]
	s_waitcnt lgkmcnt(0)
	v_mfma_f32_16x16x32_f16 v[108:111], v[124:127], v[80:83], v[108:111]
	v_mfma_f32_16x16x32_f16 v[72:75], v[144:147], v[80:83], v[72:75]
	v_mfma_f32_16x16x32_f16 v[80:83], v[54:57], v[104:107], v[112:115]
	s_waitcnt vmcnt(1)
	ds_write_b128 v19, v[212:215] offset:32768
	s_waitcnt vmcnt(0)
	ds_write_b128 v20, v[220:223] offset:32768
	v_mfma_f32_16x16x32_f16 v[112:115], v[58:61], v[104:107], v[116:119]
	v_mfma_f32_16x16x32_f16 v[116:119], v[124:127], v[104:107], v[120:123]
	s_nop 2
	ds_read_b128 v[120:123], v32 offset:22528
	v_mfma_f32_16x16x32_f16 v[34:37], v[144:147], v[104:107], v[34:37]
	ds_read_b128 v[104:107], v32 offset:20480
	s_waitcnt lgkmcnt(0)
	v_mfma_f32_16x16x32_f16 v[128:131], v[54:57], v[104:107], v[128:131]
	v_mfma_f32_16x16x32_f16 v[42:45], v[54:57], v[120:123], v[42:45]
	global_load_dwordx4 v[54:57], v[0:1], off offset:384
	v_mfma_f32_16x16x32_f16 v[132:135], v[58:61], v[104:107], v[132:135]
	v_mfma_f32_16x16x32_f16 v[24:27], v[58:61], v[120:123], v[24:27]
	v_mfma_f32_16x16x32_f16 v[140:143], v[124:127], v[104:107], v[140:143]
	v_mfma_f32_16x16x32_f16 v[28:31], v[124:127], v[120:123], v[28:31]
	v_mfma_f32_16x16x32_f16 v[76:79], v[144:147], v[104:107], v[76:79]
	global_load_dwordx4 v[104:107], v[2:3], off offset:384
	global_load_dwordx4 v[154:157], v[4:5], off offset:384
	global_load_dwordx4 v[158:161], v[6:7], off offset:384
	global_load_dwordx4 v[58:61], v[8:9], off offset:384
	global_load_dwordx4 v[188:191], v[10:11], off offset:384
	global_load_dwordx4 v[192:195], v[12:13], off offset:384
	global_load_dwordx4 v[196:199], v[14:15], off offset:384
	s_waitcnt lgkmcnt(0)
	s_barrier
; #define GL_LOAD(s_, kt_) if (VAR != 1) { a##s_##0 = GL_A(0, kt_); a##s_##1 = GL_A(1, kt_); a##s_##2 = GL_A(2, kt_); a##s_##3 = GL_A(3, kt_); b##s_##0 = GL_B(0, kt_); b##s_##1 = GL_B(1, kt_); b##s_##2 = GL_B(2, kt_); b##s_##3 = GL_B(3, kt_); }
; #define LDS_STORE(s_, buf_) if (VAR != 2) { LDS_ST1(sA, 0, buf_, a##s_##0) LDS_ST1(sA, 1, buf_, a##s_##1) LDS_ST1(sA, 2, buf_, a##s_##2) LDS_ST1(sA, 3, buf_, a##s_##3) LDS_ST1(sB, 0, buf_, b##s_##0) LDS_ST1(sB, 1, buf_, b##s_##1) LDS_ST1(sB, 2, buf_, b##s_##2) LDS_ST1(sB, 3, buf_, b##s_##3) }
;     ...
;   GL_LOAD(0, 0)
;   GL_LOAD(1, 1)
;   LDS_STORE(0, 0)
;   if (VAR != 4) __syncthreads();
; #pragma unroll
;   for (int kt = 0; kt < nk; kt += 2) {
;     if (kt + 2 < nk) { GL_LOAD(0, kt + 2) }
;     MMA_TILE(0)
;     LDS_STORE(1, 1)
;     if (VAR != 4) __syncthreads();
;     if (kt + 3 < nk) { GL_LOAD(1, kt + 3) }
;     MMA_TILE(1)
;     if (kt + 2 < nk) { LDS_STORE(0, 0) }
;     if (VAR != 4) __syncthreads();
	v_mfma_f32_16x16x32_f16 v[50:53], v[144:147], v[120:123], v[50:53]
	ds_read_b128 v[124:127], v16 offset:32768
	ds_read_b128 v[136:139], v21
	s_waitcnt lgkmcnt(0)
	v_mfma_f32_16x16x32_f16 v[38:41], v[124:127], v[136:139], v[38:41]
	ds_read_b128 v[120:123], v16 offset:34816
	ds_read_b128 v[144:147], v21 offset:2048
	s_waitcnt lgkmcnt(0)
	v_mfma_f32_16x16x32_f16 v[80:83], v[124:127], v[144:147], v[80:83]
	ds_read_b128 v[162:165], v16 offset:36864
	v_mfma_f32_16x16x32_f16 v[46:49], v[120:123], v[136:139], v[46:49]
	ds_read_b128 v[166:169], v16 offset:38912
	v_mfma_f32_16x16x32_f16 v[112:115], v[120:123], v[144:147], v[112:115]
	s_waitcnt vmcnt(7)
	ds_write_b128 v17, v[54:57] offset:16384
	s_waitcnt lgkmcnt(2)
	v_mfma_f32_16x16x32_f16 v[108:111], v[162:165], v[136:139], v[108:111]
	s_waitcnt vmcnt(6)
	ds_write_b128 v18, v[104:107] offset:16384
	v_mfma_f32_16x16x32_f16 v[116:119], v[162:165], v[144:147], v[116:119]
	s_waitcnt vmcnt(5)
	ds_write_b128 v19, v[154:157] offset:16384
	s_waitcnt lgkmcnt(3)
	v_mfma_f32_16x16x32_f16 v[72:75], v[166:169], v[136:139], v[72:75]
	ds_read_b128 v[136:139], v21 offset:4096
	v_mfma_f32_16x16x32_f16 v[34:37], v[166:169], v[144:147], v[34:37]
	ds_read_b128 v[144:147], v21 offset:6144
	s_waitcnt lgkmcnt(1)
	v_mfma_f32_16x16x32_f16 v[128:131], v[124:127], v[136:139], v[128:131]
	s_waitcnt vmcnt(4)
	ds_write_b128 v20, v[158:161] offset:16384
	s_waitcnt lgkmcnt(1)
	v_mfma_f32_16x16x32_f16 v[42:45], v[124:127], v[144:147], v[42:45]
	ds_read_b128 v[124:127], v22 offset:34816
	v_mfma_f32_16x16x32_f16 v[132:135], v[120:123], v[136:139], v[132:135]
	s_waitcnt vmcnt(3)
	ds_write_b128 v17, v[58:61] offset:49152
	v_mfma_f32_16x16x32_f16 v[24:27], v[120:123], v[144:147], v[24:27]
	ds_read_b128 v[120:123], v22 offset:32768
	v_mfma_f32_16x16x32_f16 v[140:143], v[162:165], v[136:139], v[140:143]
	s_waitcnt vmcnt(2)
	ds_write_b128 v18, v[188:191] offset:49152
	v_mfma_f32_16x16x32_f16 v[28:31], v[162:165], v[144:147], v[28:31]
	ds_read_b128 v[162:165], v22 offset:36864
	v_mfma_f32_16x16x32_f16 v[76:79], v[166:169], v[136:139], v[76:79]
	ds_read_b128 v[136:139], v32
	v_mfma_f32_16x16x32_f16 v[50:53], v[166:169], v[144:147], v[50:53]
	ds_read_b128 v[144:147], v32 offset:2048
	s_waitcnt lgkmcnt(1)
	v_mfma_f32_16x16x32_f16 v[38:41], v[120:123], v[136:139], v[38:41]
	ds_read_b128 v[166:169], v22 offset:38912
	s_waitcnt lgkmcnt(1)
	v_mfma_f32_16x16x32_f16 v[80:83], v[120:123], v[144:147], v[80:83]
	s_waitcnt vmcnt(1)
	ds_write_b128 v19, v[192:195] offset:49152
	v_mfma_f32_16x16x32_f16 v[46:49], v[124:127], v[136:139], v[46:49]
	s_waitcnt vmcnt(0)
	ds_write_b128 v20, v[196:199] offset:49152
	v_mfma_f32_16x16x32_f16 v[112:115], v[124:127], v[144:147], v[112:115]
	v_mfma_f32_16x16x32_f16 v[108:111], v[162:165], v[136:139], v[108:111]
	v_mfma_f32_16x16x32_f16 v[116:119], v[162:165], v[144:147], v[116:119]
	s_waitcnt lgkmcnt(2)
	v_mfma_f32_16x16x32_f16 v[72:75], v[166:169], v[136:139], v[72:75]
	ds_read_b128 v[136:139], v32 offset:4096
	v_mfma_f32_16x16x32_f16 v[34:37], v[166:169], v[144:147], v[34:37]
	ds_read_b128 v[144:147], v32 offset:6144
	s_waitcnt lgkmcnt(1)
	v_mfma_f32_16x16x32_f16 v[128:131], v[120:123], v[136:139], v[128:131]
	s_waitcnt lgkmcnt(0)
	v_mfma_f32_16x16x32_f16 v[42:45], v[120:123], v[144:147], v[42:45]
	global_load_dwordx4 v[120:123], v[0:1], off offset:512
	v_mfma_f32_16x16x32_f16 v[132:135], v[124:127], v[136:139], v[132:135]
	v_mfma_f32_16x16x32_f16 v[24:27], v[124:127], v[144:147], v[24:27]
	v_mfma_f32_16x16x32_f16 v[140:143], v[162:165], v[136:139], v[140:143]
	v_mfma_f32_16x16x32_f16 v[28:31], v[162:165], v[144:147], v[28:31]
	v_mfma_f32_16x16x32_f16 v[76:79], v[166:169], v[136:139], v[76:79]
	global_load_dwordx4 v[136:139], v[2:3], off offset:512
	global_load_dwordx4 v[200:203], v[4:5], off offset:512
	global_load_dwordx4 v[204:207], v[6:7], off offset:512
	global_load_dwordx4 v[124:127], v[8:9], off offset:512
	global_load_dwordx4 v[208:211], v[10:11], off offset:512
	global_load_dwordx4 v[212:215], v[12:13], off offset:512
	global_load_dwordx4 v[220:223], v[14:15], off offset:512
	s_waitcnt lgkmcnt(0)
	s_barrier
	v_mfma_f32_16x16x32_f16 v[50:53], v[166:169], v[144:147], v[50:53]
	ds_read_b128 v[54:57], v16 offset:49152
	ds_read_b128 v[104:107], v21 offset:16384
	s_waitcnt lgkmcnt(0)
	v_mfma_f32_16x16x32_f16 v[38:41], v[54:57], v[104:107], v[38:41]
	ds_read_b128 v[58:61], v16 offset:51200
	ds_read_b128 v[144:147], v21 offset:18432
	s_waitcnt lgkmcnt(0)
	v_mfma_f32_16x16x32_f16 v[80:83], v[54:57], v[144:147], v[80:83]
	ds_read_b128 v[154:157], v16 offset:53248
	v_mfma_f32_16x16x32_f16 v[46:49], v[58:61], v[104:107], v[46:49]
	ds_read_b128 v[158:161], v16 offset:55296
	s_waitcnt lgkmcnt(1)
	v_mfma_f32_16x16x32_f16 v[108:111], v[154:157], v[104:107], v[108:111]
	s_waitcnt lgkmcnt(0)
	v_mfma_f32_16x16x32_f16 v[72:75], v[158:161], v[104:107], v[72:75]
	v_mfma_f32_16x16x32_f16 v[104:107], v[58:61], v[144:147], v[112:115]
	s_waitcnt vmcnt(7)
	ds_write_b128 v17, v[120:123]
	s_waitcnt vmcnt(6)
	ds_write_b128 v18, v[136:139]
	v_mfma_f32_16x16x32_f16 v[112:115], v[154:157], v[144:147], v[116:119]
	s_nop 2
	ds_read_b128 v[116:119], v21 offset:20480
	s_waitcnt vmcnt(5)
	ds_write_b128 v19, v[200:203]
	v_mfma_f32_16x16x32_f16 v[34:37], v[158:161], v[144:147], v[34:37]
	ds_read_b128 v[144:147], v21 offset:22528
	s_waitcnt lgkmcnt(2)
	v_mfma_f32_16x16x32_f16 v[128:131], v[54:57], v[116:119], v[128:131]
	s_waitcnt vmcnt(4)
	ds_write_b128 v20, v[204:207]
	s_waitcnt lgkmcnt(1)
	v_mfma_f32_16x16x32_f16 v[42:45], v[54:57], v[144:147], v[42:45]
	ds_read_b128 v[54:57], v22 offset:49152
	v_mfma_f32_16x16x32_f16 v[132:135], v[58:61], v[116:119], v[132:135]
	s_waitcnt vmcnt(3)
; #define GL_LOAD(s_, kt_) if (VAR != 1) { a##s_##0 = GL_A(0, kt_); a##s_##1 = GL_A(1, kt_); a##s_##2 = GL_A(2, kt_); a##s_##3 = GL_A(3, kt_); b##s_##0 = GL_B(0, kt_); b##s_##1 = GL_B(1, kt_); b##s_##2 = GL_B(2, kt_); b##s_##3 = GL_B(3, kt_); }
; #define LDS_STORE(s_, buf_) if (VAR != 2) { LDS_ST1(sA, 0, buf_, a##s_##0) LDS_ST1(sA, 1, buf_, a##s_##1) LDS_ST1(sA, 2, buf_, a##s_##2) LDS_ST1(sA, 3, buf_, a##s_##3) LDS_ST1(sB, 0, buf_, b##s_##0) LDS_ST1(sB, 1, buf_, b##s_##1) LDS_ST1(sB, 2, buf_, b##s_##2) LDS_ST1(sB, 3, buf_, b##s_##3) }
;     ...
;   GL_LOAD(0, 0)
;   GL_LOAD(1, 1)
;   LDS_STORE(0, 0)
;   if (VAR != 4) __syncthreads();
; #pragma unroll
;   for (int kt = 0; kt < nk; kt += 2) {
;     if (kt + 2 < nk) { GL_LOAD(0, kt + 2) }
;     MMA_TILE(0)
;     LDS_STORE(1, 1)
;     if (VAR != 4) __syncthreads();
;     if (kt + 3 < nk) { GL_LOAD(1, kt + 3) }
;     MMA_TILE(1)
;     if (kt + 2 < nk) { LDS_STORE(0, 0) }
;     if (VAR != 4) __syncthreads();
	ds_write_b128 v17, v[124:127] offset:32768
	v_mfma_f32_16x16x32_f16 v[24:27], v[58:61], v[144:147], v[24:27]
	ds_read_b128 v[58:61], v22 offset:51200
	v_mfma_f32_16x16x32_f16 v[140:143], v[154:157], v[116:119], v[140:143]
	s_waitcnt vmcnt(2)
	ds_write_b128 v18, v[208:211] offset:32768
	v_mfma_f32_16x16x32_f16 v[28:31], v[154:157], v[144:147], v[28:31]
	ds_read_b128 v[154:157], v22 offset:53248
	v_mfma_f32_16x16x32_f16 v[76:79], v[158:161], v[116:119], v[76:79]
	ds_read_b128 v[116:119], v32 offset:16384
	v_mfma_f32_16x16x32_f16 v[50:53], v[158:161], v[144:147], v[50:53]
	ds_read_b128 v[144:147], v32 offset:18432
	s_waitcnt lgkmcnt(1)
	v_mfma_f32_16x16x32_f16 v[38:41], v[54:57], v[116:119], v[38:41]
	ds_read_b128 v[158:161], v22 offset:55296
	s_waitcnt lgkmcnt(1)
	v_mfma_f32_16x16x32_f16 v[80:83], v[54:57], v[144:147], v[80:83]
	s_waitcnt vmcnt(1)
	ds_write_b128 v19, v[212:215] offset:32768
	v_mfma_f32_16x16x32_f16 v[46:49], v[58:61], v[116:119], v[46:49]
	s_waitcnt vmcnt(0)
	ds_write_b128 v20, v[220:223] offset:32768
	v_mfma_f32_16x16x32_f16 v[104:107], v[58:61], v[144:147], v[104:107]
	v_mfma_f32_16x16x32_f16 v[108:111], v[154:157], v[116:119], v[108:111]
	v_mfma_f32_16x16x32_f16 v[112:115], v[154:157], v[144:147], v[112:115]
	s_waitcnt lgkmcnt(2)
	v_mfma_f32_16x16x32_f16 v[72:75], v[158:161], v[116:119], v[72:75]
	ds_read_b128 v[116:119], v32 offset:20480
	v_mfma_f32_16x16x32_f16 v[34:37], v[158:161], v[144:147], v[34:37]
	ds_read_b128 v[144:147], v32 offset:22528
	s_waitcnt lgkmcnt(1)
	v_mfma_f32_16x16x32_f16 v[128:131], v[54:57], v[116:119], v[128:131]
	s_waitcnt lgkmcnt(0)
	v_mfma_f32_16x16x32_f16 v[42:45], v[54:57], v[144:147], v[42:45]
	global_load_dwordx4 v[54:57], v[0:1], off offset:640
	v_mfma_f32_16x16x32_f16 v[132:135], v[58:61], v[116:119], v[132:135]
	v_mfma_f32_16x16x32_f16 v[24:27], v[58:61], v[144:147], v[24:27]
	v_mfma_f32_16x16x32_f16 v[140:143], v[154:157], v[116:119], v[140:143]
	v_mfma_f32_16x16x32_f16 v[28:31], v[154:157], v[144:147], v[28:31]
	v_mfma_f32_16x16x32_f16 v[76:79], v[158:161], v[116:119], v[76:79]
	global_load_dwordx4 v[116:119], v[2:3], off offset:640
	global_load_dwordx4 v[162:165], v[4:5], off offset:640
	global_load_dwordx4 v[166:169], v[6:7], off offset:640
	global_load_dwordx4 v[58:61], v[8:9], off offset:640
	global_load_dwordx4 v[188:191], v[10:11], off offset:640
	global_load_dwordx4 v[192:195], v[12:13], off offset:640
	global_load_dwordx4 v[196:199], v[14:15], off offset:640
	s_waitcnt lgkmcnt(0)
	s_barrier
	v_mfma_f32_16x16x32_f16 v[50:53], v[158:161], v[144:147], v[50:53]
	ds_read_b128 v[120:123], v16 offset:32768
	ds_read_b128 v[136:139], v21
	s_waitcnt lgkmcnt(0)
	v_mfma_f32_16x16x32_f16 v[38:41], v[120:123], v[136:139], v[38:41]
	ds_read_b128 v[124:127], v16 offset:34816
	ds_read_b128 v[144:147], v21 offset:2048
	s_waitcnt lgkmcnt(0)
	v_mfma_f32_16x16x32_f16 v[80:83], v[120:123], v[144:147], v[80:83]
	ds_read_b128 v[154:157], v16 offset:36864
	v_mfma_f32_16x16x32_f16 v[46:49], v[124:127], v[136:139], v[46:49]
	ds_read_b128 v[158:161], v16 offset:38912
	v_mfma_f32_16x16x32_f16 v[104:107], v[124:127], v[144:147], v[104:107]
	s_waitcnt vmcnt(7)
	ds_write_b128 v17, v[54:57] offset:16384
	s_waitcnt lgkmcnt(2)
	v_mfma_f32_16x16x32_f16 v[108:111], v[154:157], v[136:139], v[108:111]
	s_waitcnt vmcnt(6)
	ds_write_b128 v18, v[116:119] offset:16384
	v_mfma_f32_16x16x32_f16 v[112:115], v[154:157], v[144:147], v[112:115]
	s_waitcnt vmcnt(5)
	ds_write_b128 v19, v[162:165] offset:16384
	s_waitcnt lgkmcnt(3)
	v_mfma_f32_16x16x32_f16 v[72:75], v[158:161], v[136:139], v[72:75]
	ds_read_b128 v[136:139], v21 offset:4096
	v_mfma_f32_16x16x32_f16 v[34:37], v[158:161], v[144:147], v[34:37]
	ds_read_b128 v[144:147], v21 offset:6144
	s_waitcnt lgkmcnt(1)
	v_mfma_f32_16x16x32_f16 v[128:131], v[120:123], v[136:139], v[128:131]
	s_waitcnt vmcnt(4)
	ds_write_b128 v20, v[166:169] offset:16384
	s_waitcnt lgkmcnt(1)
	v_mfma_f32_16x16x32_f16 v[42:45], v[120:123], v[144:147], v[42:45]
	ds_read_b128 v[120:123], v22 offset:32768
	v_mfma_f32_16x16x32_f16 v[132:135], v[124:127], v[136:139], v[132:135]
	s_waitcnt vmcnt(3)
	ds_write_b128 v17, v[58:61] offset:49152
	v_mfma_f32_16x16x32_f16 v[24:27], v[124:127], v[144:147], v[24:27]
	ds_read_b128 v[124:127], v22 offset:34816
	v_mfma_f32_16x16x32_f16 v[140:143], v[154:157], v[136:139], v[140:143]
	s_waitcnt vmcnt(2)
	ds_write_b128 v18, v[188:191] offset:49152
	v_mfma_f32_16x16x32_f16 v[28:31], v[154:157], v[144:147], v[28:31]
	ds_read_b128 v[154:157], v22 offset:36864
	v_mfma_f32_16x16x32_f16 v[76:79], v[158:161], v[136:139], v[76:79]
	ds_read_b128 v[136:139], v32
	v_mfma_f32_16x16x32_f16 v[50:53], v[158:161], v[144:147], v[50:53]
	ds_read_b128 v[144:147], v32 offset:2048
	s_waitcnt lgkmcnt(1)
	v_mfma_f32_16x16x32_f16 v[38:41], v[120:123], v[136:139], v[38:41]
	ds_read_b128 v[158:161], v22 offset:38912
	s_waitcnt lgkmcnt(1)
	v_mfma_f32_16x16x32_f16 v[80:83], v[120:123], v[144:147], v[80:83]
	s_waitcnt vmcnt(1)
	ds_write_b128 v19, v[192:195] offset:49152
	v_mfma_f32_16x16x32_f16 v[46:49], v[124:127], v[136:139], v[46:49]
	s_waitcnt vmcnt(0)
	ds_write_b128 v20, v[196:199] offset:49152
	v_mfma_f32_16x16x32_f16 v[104:107], v[124:127], v[144:147], v[104:107]
	v_mfma_f32_16x16x32_f16 v[108:111], v[154:157], v[136:139], v[108:111]
	v_mfma_f32_16x16x32_f16 v[112:115], v[154:157], v[144:147], v[112:115]
	s_waitcnt lgkmcnt(2)
	v_mfma_f32_16x16x32_f16 v[72:75], v[158:161], v[136:139], v[72:75]
	ds_read_b128 v[136:139], v32 offset:4096
	v_mfma_f32_16x16x32_f16 v[34:37], v[158:161], v[144:147], v[34:37]
	ds_read_b128 v[144:147], v32 offset:6144
	s_waitcnt lgkmcnt(1)
	v_mfma_f32_16x16x32_f16 v[128:131], v[120:123], v[136:139], v[128:131]
	s_waitcnt lgkmcnt(0)
	v_mfma_f32_16x16x32_f16 v[42:45], v[120:123], v[144:147], v[42:45]
	global_load_dwordx4 v[120:123], v[0:1], off offset:768
	v_mfma_f32_16x16x32_f16 v[132:135], v[124:127], v[136:139], v[132:135]
	v_mfma_f32_16x16x32_f16 v[24:27], v[124:127], v[144:147], v[24:27]
	v_mfma_f32_16x16x32_f16 v[140:143], v[154:157], v[136:139], v[140:143]
	v_mfma_f32_16x16x32_f16 v[28:31], v[154:157], v[144:147], v[28:31]
	v_mfma_f32_16x16x32_f16 v[76:79], v[158:161], v[136:139], v[76:79]
	global_load_dwordx4 v[136:139], v[2:3], off offset:768
	global_load_dwordx4 v[200:203], v[4:5], off offset:768
	global_load_dwordx4 v[204:207], v[6:7], off offset:768
	global_load_dwordx4 v[124:127], v[8:9], off offset:768
	global_load_dwordx4 v[208:211], v[10:11], off offset:768
	global_load_dwordx4 v[212:215], v[12:13], off offset:768
	global_load_dwordx4 v[220:223], v[14:15], off offset:768
	s_waitcnt lgkmcnt(0)
	s_barrier
; #define GL_LOAD(s_, kt_) if (VAR != 1) { a##s_##0 = GL_A(0, kt_); a##s_##1 = GL_A(1, kt_); a##s_##2 = GL_A(2, kt_); a##s_##3 = GL_A(3, kt_); b##s_##0 = GL_B(0, kt_); b##s_##1 = GL_B(1, kt_); b##s_##2 = GL_B(2, kt_); b##s_##3 = GL_B(3, kt_); }
; #define LDS_STORE(s_, buf_) if (VAR != 2) { LDS_ST1(sA, 0, buf_, a##s_##0) LDS_ST1(sA, 1, buf_, a##s_##1) LDS_ST1(sA, 2, buf_, a##s_##2) LDS_ST1(sA, 3, buf_, a##s_##3) LDS_ST1(sB, 0, buf_, b##s_##0) LDS_ST1(sB, 1, buf_, b##s_##1) LDS_ST1(sB, 2, buf_, b##s_##2) LDS_ST1(sB, 3, buf_, b##s_##3) }
;     ...
;   GL_LOAD(0, 0)
;   GL_LOAD(1, 1)
;   LDS_STORE(0, 0)
;   if (VAR != 4) __syncthreads();
; #pragma unroll
;   for (int kt = 0; kt < nk; kt += 2) {
;     if (kt + 2 < nk) { GL_LOAD(0, kt + 2) }
;     MMA_TILE(0)
;     LDS_STORE(1, 1)
;     if (VAR != 4) __syncthreads();
;     if (kt + 3 < nk) { GL_LOAD(1, kt + 3) }
;     MMA_TILE(1)
;     if (kt + 2 < nk) { LDS_STORE(0, 0) }
;     if (VAR != 4) __syncthreads();
	v_mfma_f32_16x16x32_f16 v[50:53], v[158:161], v[144:147], v[50:53]
	ds_read_b128 v[54:57], v16 offset:49152
	ds_read_b128 v[116:119], v21 offset:16384
	s_waitcnt lgkmcnt(0)
	v_mfma_f32_16x16x32_f16 v[38:41], v[54:57], v[116:119], v[38:41]
	ds_read_b128 v[58:61], v16 offset:51200
	ds_read_b128 v[144:147], v21 offset:18432
	s_waitcnt lgkmcnt(0)
	v_mfma_f32_16x16x32_f16 v[80:83], v[54:57], v[144:147], v[80:83]
	ds_read_b128 v[154:157], v16 offset:53248
	v_mfma_f32_16x16x32_f16 v[46:49], v[58:61], v[116:119], v[46:49]
	ds_read_b128 v[158:161], v16 offset:55296
	v_mfma_f32_16x16x32_f16 v[104:107], v[58:61], v[144:147], v[104:107]
	s_waitcnt vmcnt(7)
	ds_write_b128 v17, v[120:123]
	s_waitcnt lgkmcnt(2)
	v_mfma_f32_16x16x32_f16 v[108:111], v[154:157], v[116:119], v[108:111]
	s_waitcnt vmcnt(6)
	ds_write_b128 v18, v[136:139]
	v_mfma_f32_16x16x32_f16 v[112:115], v[154:157], v[144:147], v[112:115]
	s_waitcnt vmcnt(5)
	ds_write_b128 v19, v[200:203]
	s_waitcnt lgkmcnt(3)
	v_mfma_f32_16x16x32_f16 v[72:75], v[158:161], v[116:119], v[72:75]
	ds_read_b128 v[116:119], v21 offset:20480
	v_mfma_f32_16x16x32_f16 v[34:37], v[158:161], v[144:147], v[34:37]
	ds_read_b128 v[144:147], v21 offset:22528
	s_waitcnt lgkmcnt(1)
	v_mfma_f32_16x16x32_f16 v[128:131], v[54:57], v[116:119], v[128:131]
	s_waitcnt vmcnt(4)
	ds_write_b128 v20, v[204:207]
	s_waitcnt lgkmcnt(1)
	v_mfma_f32_16x16x32_f16 v[42:45], v[54:57], v[144:147], v[42:45]
	ds_read_b128 v[54:57], v22 offset:49152
	v_mfma_f32_16x16x32_f16 v[132:135], v[58:61], v[116:119], v[132:135]
	s_waitcnt vmcnt(3)
	ds_write_b128 v17, v[124:127] offset:32768
	v_mfma_f32_16x16x32_f16 v[24:27], v[58:61], v[144:147], v[24:27]
	ds_read_b128 v[58:61], v22 offset:51200
	v_mfma_f32_16x16x32_f16 v[140:143], v[154:157], v[116:119], v[140:143]
	s_waitcnt vmcnt(2)
	ds_write_b128 v18, v[208:211] offset:32768
	v_mfma_f32_16x16x32_f16 v[28:31], v[154:157], v[144:147], v[28:31]
	ds_read_b128 v[154:157], v22 offset:53248
	v_mfma_f32_16x16x32_f16 v[76:79], v[158:161], v[116:119], v[76:79]
	ds_read_b128 v[116:119], v32 offset:16384
	v_mfma_f32_16x16x32_f16 v[50:53], v[158:161], v[144:147], v[50:53]
	ds_read_b128 v[144:147], v32 offset:18432
	s_waitcnt lgkmcnt(1)
	v_mfma_f32_16x16x32_f16 v[38:41], v[54:57], v[116:119], v[38:41]
	ds_read_b128 v[158:161], v22 offset:55296
	s_waitcnt lgkmcnt(1)
	v_mfma_f32_16x16x32_f16 v[80:83], v[54:57], v[144:147], v[80:83]
	s_waitcnt vmcnt(1)
	ds_write_b128 v19, v[212:215] offset:32768
	v_mfma_f32_16x16x32_f16 v[46:49], v[58:61], v[116:119], v[46:49]
	s_waitcnt vmcnt(0)
	ds_write_b128 v20, v[220:223] offset:32768
	v_mfma_f32_16x16x32_f16 v[104:107], v[58:61], v[144:147], v[104:107]
	v_mfma_f32_16x16x32_f16 v[108:111], v[154:157], v[116:119], v[108:111]
	v_mfma_f32_16x16x32_f16 v[112:115], v[154:157], v[144:147], v[112:115]
	s_waitcnt lgkmcnt(2)
	v_mfma_f32_16x16x32_f16 v[72:75], v[158:161], v[116:119], v[72:75]
	ds_read_b128 v[116:119], v32 offset:20480
	v_mfma_f32_16x16x32_f16 v[34:37], v[158:161], v[144:147], v[34:37]
	ds_read_b128 v[144:147], v32 offset:22528
	s_waitcnt lgkmcnt(1)
	v_mfma_f32_16x16x32_f16 v[128:131], v[54:57], v[116:119], v[128:131]
	s_waitcnt lgkmcnt(0)
	v_mfma_f32_16x16x32_f16 v[42:45], v[54:57], v[144:147], v[42:45]
	global_load_dwordx4 v[54:57], v[0:1], off offset:896
	v_mfma_f32_16x16x32_f16 v[132:135], v[58:61], v[116:119], v[132:135]
	v_mfma_f32_16x16x32_f16 v[24:27], v[58:61], v[144:147], v[24:27]
	v_mfma_f32_16x16x32_f16 v[140:143], v[154:157], v[116:119], v[140:143]
	v_mfma_f32_16x16x32_f16 v[28:31], v[154:157], v[144:147], v[28:31]
	v_mfma_f32_16x16x32_f16 v[76:79], v[158:161], v[116:119], v[76:79]
	global_load_dwordx4 v[116:119], v[2:3], off offset:896
	global_load_dwordx4 v[162:165], v[4:5], off offset:896
	global_load_dwordx4 v[166:169], v[6:7], off offset:896
	global_load_dwordx4 v[58:61], v[8:9], off offset:896
	global_load_dwordx4 v[188:191], v[10:11], off offset:896
	global_load_dwordx4 v[192:195], v[12:13], off offset:896
	global_load_dwordx4 v[196:199], v[14:15], off offset:896
	s_waitcnt lgkmcnt(0)
	s_barrier
	v_mfma_f32_16x16x32_f16 v[50:53], v[158:161], v[144:147], v[50:53]
	ds_read_b128 v[120:123], v16 offset:32768
	ds_read_b128 v[136:139], v21
	s_waitcnt lgkmcnt(0)
	v_mfma_f32_16x16x32_f16 v[38:41], v[120:123], v[136:139], v[38:41]
	ds_read_b128 v[124:127], v16 offset:34816
	ds_read_b128 v[144:147], v21 offset:2048
	s_waitcnt lgkmcnt(0)
	v_mfma_f32_16x16x32_f16 v[80:83], v[120:123], v[144:147], v[80:83]
	ds_read_b128 v[154:157], v16 offset:36864
	v_mfma_f32_16x16x32_f16 v[46:49], v[124:127], v[136:139], v[46:49]
	ds_read_b128 v[158:161], v16 offset:38912
	v_mfma_f32_16x16x32_f16 v[104:107], v[124:127], v[144:147], v[104:107]
	s_waitcnt vmcnt(7)
	ds_write_b128 v17, v[54:57] offset:16384
	s_waitcnt lgkmcnt(2)
	v_mfma_f32_16x16x32_f16 v[108:111], v[154:157], v[136:139], v[108:111]
	s_waitcnt vmcnt(6)
	ds_write_b128 v18, v[116:119] offset:16384
	v_mfma_f32_16x16x32_f16 v[112:115], v[154:157], v[144:147], v[112:115]
	s_waitcnt vmcnt(5)
	ds_write_b128 v19, v[162:165] offset:16384
	s_waitcnt lgkmcnt(3)
	v_mfma_f32_16x16x32_f16 v[72:75], v[158:161], v[136:139], v[72:75]
	ds_read_b128 v[136:139], v21 offset:4096
	v_mfma_f32_16x16x32_f16 v[34:37], v[158:161], v[144:147], v[34:37]
	ds_read_b128 v[144:147], v21 offset:6144
	s_waitcnt lgkmcnt(1)
	v_mfma_f32_16x16x32_f16 v[128:131], v[120:123], v[136:139], v[128:131]
	s_waitcnt vmcnt(4)
	ds_write_b128 v20, v[166:169] offset:16384
	s_waitcnt lgkmcnt(1)
	v_mfma_f32_16x16x32_f16 v[42:45], v[120:123], v[144:147], v[42:45]
	ds_read_b128 v[120:123], v22 offset:32768
	v_mfma_f32_16x16x32_f16 v[132:135], v[124:127], v[136:139], v[132:135]
	s_waitcnt vmcnt(3)
; #define GL_LOAD(s_, kt_) if (VAR != 1) { a##s_##0 = GL_A(0, kt_); a##s_##1 = GL_A(1, kt_); a##s_##2 = GL_A(2, kt_); a##s_##3 = GL_A(3, kt_); b##s_##0 = GL_B(0, kt_); b##s_##1 = GL_B(1, kt_); b##s_##2 = GL_B(2, kt_); b##s_##3 = GL_B(3, kt_); }
; #define LDS_STORE(s_, buf_) if (VAR != 2) { LDS_ST1(sA, 0, buf_, a##s_##0) LDS_ST1(sA, 1, buf_, a##s_##1) LDS_ST1(sA, 2, buf_, a##s_##2) LDS_ST1(sA, 3, buf_, a##s_##3) LDS_ST1(sB, 0, buf_, b##s_##0) LDS_ST1(sB, 1, buf_, b##s_##1) LDS_ST1(sB, 2, buf_, b##s_##2) LDS_ST1(sB, 3, buf_, b##s_##3) }
;     ...
;   GL_LOAD(0, 0)
;   GL_LOAD(1, 1)
;   LDS_STORE(0, 0)
;   if (VAR != 4) __syncthreads();
; #pragma unroll
;   for (int kt = 0; kt < nk; kt += 2) {
;     if (kt + 2 < nk) { GL_LOAD(0, kt + 2) }
;     MMA_TILE(0)
;     LDS_STORE(1, 1)
;     if (VAR != 4) __syncthreads();
;     if (kt + 3 < nk) { GL_LOAD(1, kt + 3) }
;     MMA_TILE(1)
;     if (kt + 2 < nk) { LDS_STORE(0, 0) }
;     if (VAR != 4) __syncthreads();
	ds_write_b128 v17, v[58:61] offset:49152
	v_mfma_f32_16x16x32_f16 v[24:27], v[124:127], v[144:147], v[24:27]
	ds_read_b128 v[124:127], v22 offset:34816
	v_mfma_f32_16x16x32_f16 v[140:143], v[154:157], v[136:139], v[140:143]
	s_waitcnt vmcnt(2)
	ds_write_b128 v18, v[188:191] offset:49152
	v_mfma_f32_16x16x32_f16 v[28:31], v[154:157], v[144:147], v[28:31]
	ds_read_b128 v[154:157], v22 offset:36864
	v_mfma_f32_16x16x32_f16 v[76:79], v[158:161], v[136:139], v[76:79]
	ds_read_b128 v[136:139], v32
	v_mfma_f32_16x16x32_f16 v[50:53], v[158:161], v[144:147], v[50:53]
	ds_read_b128 v[144:147], v32 offset:2048
	s_waitcnt lgkmcnt(1)
	v_mfma_f32_16x16x32_f16 v[38:41], v[120:123], v[136:139], v[38:41]
	ds_read_b128 v[158:161], v22 offset:38912
	s_waitcnt lgkmcnt(1)
	v_mfma_f32_16x16x32_f16 v[80:83], v[120:123], v[144:147], v[80:83]
	s_waitcnt vmcnt(1)
	ds_write_b128 v19, v[192:195] offset:49152
	v_mfma_f32_16x16x32_f16 v[46:49], v[124:127], v[136:139], v[46:49]
	s_waitcnt vmcnt(0)
	ds_write_b128 v20, v[196:199] offset:49152
	v_mfma_f32_16x16x32_f16 v[104:107], v[124:127], v[144:147], v[104:107]
	v_mfma_f32_16x16x32_f16 v[108:111], v[154:157], v[136:139], v[108:111]
	v_mfma_f32_16x16x32_f16 v[112:115], v[154:157], v[144:147], v[112:115]
	s_waitcnt lgkmcnt(2)
	v_mfma_f32_16x16x32_f16 v[72:75], v[158:161], v[136:139], v[72:75]
	ds_read_b128 v[136:139], v32 offset:4096
	v_mfma_f32_16x16x32_f16 v[34:37], v[158:161], v[144:147], v[34:37]
	ds_read_b128 v[144:147], v32 offset:6144
	s_waitcnt lgkmcnt(1)
	v_mfma_f32_16x16x32_f16 v[128:131], v[120:123], v[136:139], v[128:131]
	s_waitcnt lgkmcnt(0)
	v_mfma_f32_16x16x32_f16 v[42:45], v[120:123], v[144:147], v[42:45]
	global_load_dwordx4 v[120:123], v[0:1], off offset:1024
	v_mfma_f32_16x16x32_f16 v[132:135], v[124:127], v[136:139], v[132:135]
	v_mfma_f32_16x16x32_f16 v[24:27], v[124:127], v[144:147], v[24:27]
	v_mfma_f32_16x16x32_f16 v[140:143], v[154:157], v[136:139], v[140:143]
	v_mfma_f32_16x16x32_f16 v[28:31], v[154:157], v[144:147], v[28:31]
	v_mfma_f32_16x16x32_f16 v[76:79], v[158:161], v[136:139], v[76:79]
	global_load_dwordx4 v[136:139], v[2:3], off offset:1024
	global_load_dwordx4 v[200:203], v[4:5], off offset:1024
	global_load_dwordx4 v[204:207], v[6:7], off offset:1024
	global_load_dwordx4 v[124:127], v[8:9], off offset:1024
	global_load_dwordx4 v[208:211], v[10:11], off offset:1024
	global_load_dwordx4 v[212:215], v[12:13], off offset:1024
	global_load_dwordx4 v[220:223], v[14:15], off offset:1024
	s_waitcnt lgkmcnt(0)
	s_barrier
	v_mfma_f32_16x16x32_f16 v[50:53], v[158:161], v[144:147], v[50:53]
	ds_read_b128 v[54:57], v16 offset:49152
	ds_read_b128 v[116:119], v21 offset:16384
	s_waitcnt lgkmcnt(0)
	v_mfma_f32_16x16x32_f16 v[38:41], v[54:57], v[116:119], v[38:41]
	ds_read_b128 v[58:61], v16 offset:51200
	ds_read_b128 v[144:147], v21 offset:18432
	s_waitcnt lgkmcnt(0)
	v_mfma_f32_16x16x32_f16 v[80:83], v[54:57], v[144:147], v[80:83]
	ds_read_b128 v[154:157], v16 offset:53248
	v_mfma_f32_16x16x32_f16 v[46:49], v[58:61], v[116:119], v[46:49]
	ds_read_b128 v[158:161], v16 offset:55296
	v_mfma_f32_16x16x32_f16 v[104:107], v[58:61], v[144:147], v[104:107]
	s_waitcnt vmcnt(7)
	ds_write_b128 v17, v[120:123]
	s_waitcnt lgkmcnt(2)
	v_mfma_f32_16x16x32_f16 v[108:111], v[154:157], v[116:119], v[108:111]
	s_waitcnt vmcnt(6)
	ds_write_b128 v18, v[136:139]
	v_mfma_f32_16x16x32_f16 v[112:115], v[154:157], v[144:147], v[112:115]
	s_waitcnt vmcnt(5)
	ds_write_b128 v19, v[200:203]
	s_waitcnt lgkmcnt(3)
	v_mfma_f32_16x16x32_f16 v[72:75], v[158:161], v[116:119], v[72:75]
	ds_read_b128 v[116:119], v21 offset:20480
	v_mfma_f32_16x16x32_f16 v[34:37], v[158:161], v[144:147], v[34:37]
	ds_read_b128 v[144:147], v21 offset:22528
	s_waitcnt lgkmcnt(1)
	v_mfma_f32_16x16x32_f16 v[128:131], v[54:57], v[116:119], v[128:131]
	s_waitcnt vmcnt(4)
	ds_write_b128 v20, v[204:207]
	s_waitcnt lgkmcnt(1)
	v_mfma_f32_16x16x32_f16 v[42:45], v[54:57], v[144:147], v[42:45]
	ds_read_b128 v[54:57], v22 offset:49152
	v_mfma_f32_16x16x32_f16 v[132:135], v[58:61], v[116:119], v[132:135]
	s_waitcnt vmcnt(3)
	ds_write_b128 v17, v[124:127] offset:32768
	v_mfma_f32_16x16x32_f16 v[24:27], v[58:61], v[144:147], v[24:27]
	ds_read_b128 v[58:61], v22 offset:51200
	v_mfma_f32_16x16x32_f16 v[140:143], v[154:157], v[116:119], v[140:143]
	s_waitcnt vmcnt(2)
	ds_write_b128 v18, v[208:211] offset:32768
	v_mfma_f32_16x16x32_f16 v[28:31], v[154:157], v[144:147], v[28:31]
	ds_read_b128 v[154:157], v22 offset:53248
	v_mfma_f32_16x16x32_f16 v[76:79], v[158:161], v[116:119], v[76:79]
	ds_read_b128 v[116:119], v32 offset:16384
	v_mfma_f32_16x16x32_f16 v[50:53], v[158:161], v[144:147], v[50:53]
	ds_read_b128 v[144:147], v32 offset:18432
	s_waitcnt lgkmcnt(1)
	v_mfma_f32_16x16x32_f16 v[38:41], v[54:57], v[116:119], v[38:41]
	ds_read_b128 v[158:161], v22 offset:55296
	s_waitcnt lgkmcnt(1)
	v_mfma_f32_16x16x32_f16 v[80:83], v[54:57], v[144:147], v[80:83]
	s_waitcnt vmcnt(1)
	ds_write_b128 v19, v[212:215] offset:32768
	v_mfma_f32_16x16x32_f16 v[46:49], v[58:61], v[116:119], v[46:49]
	s_waitcnt vmcnt(0)
	ds_write_b128 v20, v[220:223] offset:32768
	v_mfma_f32_16x16x32_f16 v[104:107], v[58:61], v[144:147], v[104:107]
	v_mfma_f32_16x16x32_f16 v[108:111], v[154:157], v[116:119], v[108:111]
	v_mfma_f32_16x16x32_f16 v[112:115], v[154:157], v[144:147], v[112:115]
	s_waitcnt lgkmcnt(2)
	v_mfma_f32_16x16x32_f16 v[72:75], v[158:161], v[116:119], v[72:75]
	ds_read_b128 v[116:119], v32 offset:20480
	v_mfma_f32_16x16x32_f16 v[34:37], v[158:161], v[144:147], v[34:37]
	ds_read_b128 v[144:147], v32 offset:22528
	s_waitcnt lgkmcnt(1)
	v_mfma_f32_16x16x32_f16 v[128:131], v[54:57], v[116:119], v[128:131]
	s_waitcnt lgkmcnt(0)
	v_mfma_f32_16x16x32_f16 v[42:45], v[54:57], v[144:147], v[42:45]
	global_load_dwordx4 v[54:57], v[0:1], off offset:1152
	v_mfma_f32_16x16x32_f16 v[132:135], v[58:61], v[116:119], v[132:135]
	v_mfma_f32_16x16x32_f16 v[24:27], v[58:61], v[144:147], v[24:27]
	v_mfma_f32_16x16x32_f16 v[140:143], v[154:157], v[116:119], v[140:143]
	v_mfma_f32_16x16x32_f16 v[28:31], v[154:157], v[144:147], v[28:31]
	v_mfma_f32_16x16x32_f16 v[76:79], v[158:161], v[116:119], v[76:79]
	global_load_dwordx4 v[116:119], v[2:3], off offset:1152
	global_load_dwordx4 v[162:165], v[4:5], off offset:1152
	global_load_dwordx4 v[166:169], v[6:7], off offset:1152
	global_load_dwordx4 v[58:61], v[8:9], off offset:1152
	global_load_dwordx4 v[188:191], v[10:11], off offset:1152
	global_load_dwordx4 v[192:195], v[12:13], off offset:1152
	global_load_dwordx4 v[196:199], v[14:15], off offset:1152
	s_waitcnt lgkmcnt(0)
	s_barrier
; #define GL_LOAD(s_, kt_) if (VAR != 1) { a##s_##0 = GL_A(0, kt_); a##s_##1 = GL_A(1, kt_); a##s_##2 = GL_A(2, kt_); a##s_##3 = GL_A(3, kt_); b##s_##0 = GL_B(0, kt_); b##s_##1 = GL_B(1, kt_); b##s_##2 = GL_B(2, kt_); b##s_##3 = GL_B(3, kt_); }
; #define LDS_STORE(s_, buf_) if (VAR != 2) { LDS_ST1(sA, 0, buf_, a##s_##0) LDS_ST1(sA, 1, buf_, a##s_##1) LDS_ST1(sA, 2, buf_, a##s_##2) LDS_ST1(sA, 3, buf_, a##s_##3) LDS_ST1(sB, 0, buf_, b##s_##0) LDS_ST1(sB, 1, buf_, b##s_##1) LDS_ST1(sB, 2, buf_, b##s_##2) LDS_ST1(sB, 3, buf_, b##s_##3) }
;     ...
;   GL_LOAD(0, 0)
;   GL_LOAD(1, 1)
;   LDS_STORE(0, 0)
;   if (VAR != 4) __syncthreads();
; #pragma unroll
;   for (int kt = 0; kt < nk; kt += 2) {
;     if (kt + 2 < nk) { GL_LOAD(0, kt + 2) }
;     MMA_TILE(0)
;     LDS_STORE(1, 1)
;     if (VAR != 4) __syncthreads();
;     if (kt + 3 < nk) { GL_LOAD(1, kt + 3) }
;     MMA_TILE(1)
;     if (kt + 2 < nk) { LDS_STORE(0, 0) }
;     if (VAR != 4) __syncthreads();
	v_mfma_f32_16x16x32_f16 v[50:53], v[158:161], v[144:147], v[50:53]
	ds_read_b128 v[120:123], v16 offset:32768
	ds_read_b128 v[136:139], v21
	s_waitcnt lgkmcnt(0)
	v_mfma_f32_16x16x32_f16 v[38:41], v[120:123], v[136:139], v[38:41]
	ds_read_b128 v[124:127], v16 offset:34816
	ds_read_b128 v[144:147], v21 offset:2048
	s_waitcnt lgkmcnt(0)
	v_mfma_f32_16x16x32_f16 v[80:83], v[120:123], v[144:147], v[80:83]
	ds_read_b128 v[154:157], v16 offset:36864
	v_mfma_f32_16x16x32_f16 v[46:49], v[124:127], v[136:139], v[46:49]
	ds_read_b128 v[158:161], v16 offset:38912
	v_mfma_f32_16x16x32_f16 v[104:107], v[124:127], v[144:147], v[104:107]
	s_waitcnt vmcnt(7)
	ds_write_b128 v17, v[54:57] offset:16384
	s_waitcnt lgkmcnt(2)
	v_mfma_f32_16x16x32_f16 v[108:111], v[154:157], v[136:139], v[108:111]
	s_waitcnt vmcnt(6)
	ds_write_b128 v18, v[116:119] offset:16384
	v_mfma_f32_16x16x32_f16 v[112:115], v[154:157], v[144:147], v[112:115]
	s_waitcnt vmcnt(5)
	ds_write_b128 v19, v[162:165] offset:16384
	s_waitcnt lgkmcnt(3)
	v_mfma_f32_16x16x32_f16 v[72:75], v[158:161], v[136:139], v[72:75]
	ds_read_b128 v[136:139], v21 offset:4096
	v_mfma_f32_16x16x32_f16 v[34:37], v[158:161], v[144:147], v[34:37]
	ds_read_b128 v[144:147], v21 offset:6144
	s_waitcnt lgkmcnt(1)
	v_mfma_f32_16x16x32_f16 v[128:131], v[120:123], v[136:139], v[128:131]
	s_waitcnt vmcnt(4)
	ds_write_b128 v20, v[166:169] offset:16384
	s_waitcnt lgkmcnt(1)
	v_mfma_f32_16x16x32_f16 v[42:45], v[120:123], v[144:147], v[42:45]
	ds_read_b128 v[120:123], v22 offset:32768
	v_mfma_f32_16x16x32_f16 v[132:135], v[124:127], v[136:139], v[132:135]
	s_waitcnt vmcnt(3)
	ds_write_b128 v17, v[58:61] offset:49152
	v_mfma_f32_16x16x32_f16 v[24:27], v[124:127], v[144:147], v[24:27]
	ds_read_b128 v[124:127], v22 offset:34816
	v_mfma_f32_16x16x32_f16 v[140:143], v[154:157], v[136:139], v[140:143]
	s_waitcnt vmcnt(2)
	ds_write_b128 v18, v[188:191] offset:49152
	v_mfma_f32_16x16x32_f16 v[28:31], v[154:157], v[144:147], v[28:31]
	ds_read_b128 v[154:157], v22 offset:36864
	v_mfma_f32_16x16x32_f16 v[76:79], v[158:161], v[136:139], v[76:79]
	ds_read_b128 v[136:139], v32
	v_mfma_f32_16x16x32_f16 v[50:53], v[158:161], v[144:147], v[50:53]
	ds_read_b128 v[144:147], v32 offset:2048
	s_waitcnt lgkmcnt(1)
	v_mfma_f32_16x16x32_f16 v[38:41], v[120:123], v[136:139], v[38:41]
	ds_read_b128 v[158:161], v22 offset:38912
	s_waitcnt lgkmcnt(1)
	v_mfma_f32_16x16x32_f16 v[80:83], v[120:123], v[144:147], v[80:83]
	s_waitcnt vmcnt(1)
	ds_write_b128 v19, v[192:195] offset:49152
	v_mfma_f32_16x16x32_f16 v[46:49], v[124:127], v[136:139], v[46:49]
	s_waitcnt vmcnt(0)
	ds_write_b128 v20, v[196:199] offset:49152
	v_mfma_f32_16x16x32_f16 v[104:107], v[124:127], v[144:147], v[104:107]
	v_mfma_f32_16x16x32_f16 v[108:111], v[154:157], v[136:139], v[108:111]
	v_mfma_f32_16x16x32_f16 v[112:115], v[154:157], v[144:147], v[112:115]
	s_waitcnt lgkmcnt(2)
	v_mfma_f32_16x16x32_f16 v[72:75], v[158:161], v[136:139], v[72:75]
	ds_read_b128 v[136:139], v32 offset:4096
	v_mfma_f32_16x16x32_f16 v[34:37], v[158:161], v[144:147], v[34:37]
	ds_read_b128 v[144:147], v32 offset:6144
	s_waitcnt lgkmcnt(1)
	v_mfma_f32_16x16x32_f16 v[128:131], v[120:123], v[136:139], v[128:131]
	s_waitcnt lgkmcnt(0)
	v_mfma_f32_16x16x32_f16 v[42:45], v[120:123], v[144:147], v[42:45]
	global_load_dwordx4 v[120:123], v[0:1], off offset:1280
	v_mfma_f32_16x16x32_f16 v[132:135], v[124:127], v[136:139], v[132:135]
	v_mfma_f32_16x16x32_f16 v[24:27], v[124:127], v[144:147], v[24:27]
	v_mfma_f32_16x16x32_f16 v[140:143], v[154:157], v[136:139], v[140:143]
	v_mfma_f32_16x16x32_f16 v[28:31], v[154:157], v[144:147], v[28:31]
	v_mfma_f32_16x16x32_f16 v[76:79], v[158:161], v[136:139], v[76:79]
	global_load_dwordx4 v[136:139], v[2:3], off offset:1280
	global_load_dwordx4 v[200:203], v[4:5], off offset:1280
	global_load_dwordx4 v[204:207], v[6:7], off offset:1280
	global_load_dwordx4 v[124:127], v[8:9], off offset:1280
	global_load_dwordx4 v[208:211], v[10:11], off offset:1280
	global_load_dwordx4 v[212:215], v[12:13], off offset:1280
	global_load_dwordx4 v[220:223], v[14:15], off offset:1280
	s_waitcnt lgkmcnt(0)
	s_barrier
	v_mfma_f32_16x16x32_f16 v[50:53], v[158:161], v[144:147], v[50:53]
	ds_read_b128 v[54:57], v16 offset:49152
	ds_read_b128 v[116:119], v21 offset:16384
	s_waitcnt lgkmcnt(0)
	v_mfma_f32_16x16x32_f16 v[38:41], v[54:57], v[116:119], v[38:41]
	ds_read_b128 v[58:61], v16 offset:51200
	ds_read_b128 v[144:147], v21 offset:18432
	s_waitcnt lgkmcnt(0)
	v_mfma_f32_16x16x32_f16 v[80:83], v[54:57], v[144:147], v[80:83]
	ds_read_b128 v[154:157], v16 offset:53248
	v_mfma_f32_16x16x32_f16 v[46:49], v[58:61], v[116:119], v[46:49]
	ds_read_b128 v[158:161], v16 offset:55296
	v_mfma_f32_16x16x32_f16 v[104:107], v[58:61], v[144:147], v[104:107]
	s_waitcnt vmcnt(7)
	ds_write_b128 v17, v[120:123]
	s_waitcnt lgkmcnt(2)
	v_mfma_f32_16x16x32_f16 v[108:111], v[154:157], v[116:119], v[108:111]
	s_waitcnt vmcnt(6)
	ds_write_b128 v18, v[136:139]
	v_mfma_f32_16x16x32_f16 v[112:115], v[154:157], v[144:147], v[112:115]
	s_waitcnt vmcnt(5)
	ds_write_b128 v19, v[200:203]
	s_waitcnt lgkmcnt(3)
	v_mfma_f32_16x16x32_f16 v[72:75], v[158:161], v[116:119], v[72:75]
	ds_read_b128 v[116:119], v21 offset:20480
	v_mfma_f32_16x16x32_f16 v[34:37], v[158:161], v[144:147], v[34:37]
	ds_read_b128 v[144:147], v21 offset:22528
	s_waitcnt lgkmcnt(1)
	v_mfma_f32_16x16x32_f16 v[128:131], v[54:57], v[116:119], v[128:131]
	s_waitcnt vmcnt(4)
	ds_write_b128 v20, v[204:207]
	s_waitcnt lgkmcnt(1)
	v_mfma_f32_16x16x32_f16 v[42:45], v[54:57], v[144:147], v[42:45]
	ds_read_b128 v[54:57], v22 offset:49152
	v_mfma_f32_16x16x32_f16 v[132:135], v[58:61], v[116:119], v[132:135]
	s_waitcnt vmcnt(3)
; #define GL_LOAD(s_, kt_) if (VAR != 1) { a##s_##0 = GL_A(0, kt_); a##s_##1 = GL_A(1, kt_); a##s_##2 = GL_A(2, kt_); a##s_##3 = GL_A(3, kt_); b##s_##0 = GL_B(0, kt_); b##s_##1 = GL_B(1, kt_); b##s_##2 = GL_B(2, kt_); b##s_##3 = GL_B(3, kt_); }
; #define LDS_STORE(s_, buf_) if (VAR != 2) { LDS_ST1(sA, 0, buf_, a##s_##0) LDS_ST1(sA, 1, buf_, a##s_##1) LDS_ST1(sA, 2, buf_, a##s_##2) LDS_ST1(sA, 3, buf_, a##s_##3) LDS_ST1(sB, 0, buf_, b##s_##0) LDS_ST1(sB, 1, buf_, b##s_##1) LDS_ST1(sB, 2, buf_, b##s_##2) LDS_ST1(sB, 3, buf_, b##s_##3) }
;     ...
;   GL_LOAD(0, 0)
;   GL_LOAD(1, 1)
;   LDS_STORE(0, 0)
;   if (VAR != 4) __syncthreads();
; #pragma unroll
;   for (int kt = 0; kt < nk; kt += 2) {
;     if (kt + 2 < nk) { GL_LOAD(0, kt + 2) }
;     MMA_TILE(0)
;     LDS_STORE(1, 1)
;     if (VAR != 4) __syncthreads();
;     if (kt + 3 < nk) { GL_LOAD(1, kt + 3) }
;     MMA_TILE(1)
;     if (kt + 2 < nk) { LDS_STORE(0, 0) }
;     if (VAR != 4) __syncthreads();
	ds_write_b128 v17, v[124:127] offset:32768
	v_mfma_f32_16x16x32_f16 v[24:27], v[58:61], v[144:147], v[24:27]
	ds_read_b128 v[58:61], v22 offset:51200
	v_mfma_f32_16x16x32_f16 v[140:143], v[154:157], v[116:119], v[140:143]
	s_waitcnt vmcnt(2)
	ds_write_b128 v18, v[208:211] offset:32768
	v_mfma_f32_16x16x32_f16 v[28:31], v[154:157], v[144:147], v[28:31]
	ds_read_b128 v[154:157], v22 offset:53248
	v_mfma_f32_16x16x32_f16 v[76:79], v[158:161], v[116:119], v[76:79]
	ds_read_b128 v[116:119], v32 offset:16384
	v_mfma_f32_16x16x32_f16 v[50:53], v[158:161], v[144:147], v[50:53]
	ds_read_b128 v[144:147], v32 offset:18432
	s_waitcnt lgkmcnt(1)
	v_mfma_f32_16x16x32_f16 v[38:41], v[54:57], v[116:119], v[38:41]
	ds_read_b128 v[158:161], v22 offset:55296
	s_waitcnt lgkmcnt(1)
	v_mfma_f32_16x16x32_f16 v[80:83], v[54:57], v[144:147], v[80:83]
	s_waitcnt vmcnt(1)
	ds_write_b128 v19, v[212:215] offset:32768
	v_mfma_f32_16x16x32_f16 v[46:49], v[58:61], v[116:119], v[46:49]
	s_waitcnt vmcnt(0)
	ds_write_b128 v20, v[220:223] offset:32768
	v_mfma_f32_16x16x32_f16 v[104:107], v[58:61], v[144:147], v[104:107]
	v_mfma_f32_16x16x32_f16 v[108:111], v[154:157], v[116:119], v[108:111]
	v_mfma_f32_16x16x32_f16 v[112:115], v[154:157], v[144:147], v[112:115]
	s_waitcnt lgkmcnt(2)
	v_mfma_f32_16x16x32_f16 v[72:75], v[158:161], v[116:119], v[72:75]
	ds_read_b128 v[116:119], v32 offset:20480
	v_mfma_f32_16x16x32_f16 v[34:37], v[158:161], v[144:147], v[34:37]
	ds_read_b128 v[144:147], v32 offset:22528
	s_waitcnt lgkmcnt(1)
	v_mfma_f32_16x16x32_f16 v[128:131], v[54:57], v[116:119], v[128:131]
	s_waitcnt lgkmcnt(0)
	v_mfma_f32_16x16x32_f16 v[42:45], v[54:57], v[144:147], v[42:45]
	global_load_dwordx4 v[54:57], v[0:1], off offset:1408
	v_mfma_f32_16x16x32_f16 v[132:135], v[58:61], v[116:119], v[132:135]
	v_mfma_f32_16x16x32_f16 v[24:27], v[58:61], v[144:147], v[24:27]
	v_mfma_f32_16x16x32_f16 v[140:143], v[154:157], v[116:119], v[140:143]
	v_mfma_f32_16x16x32_f16 v[28:31], v[154:157], v[144:147], v[28:31]
	v_mfma_f32_16x16x32_f16 v[76:79], v[158:161], v[116:119], v[76:79]
	global_load_dwordx4 v[116:119], v[2:3], off offset:1408
	global_load_dwordx4 v[162:165], v[4:5], off offset:1408
	global_load_dwordx4 v[166:169], v[6:7], off offset:1408
	global_load_dwordx4 v[58:61], v[8:9], off offset:1408
	global_load_dwordx4 v[188:191], v[10:11], off offset:1408
	global_load_dwordx4 v[192:195], v[12:13], off offset:1408
	global_load_dwordx4 v[196:199], v[14:15], off offset:1408
	s_waitcnt lgkmcnt(0)
	s_barrier
	v_mfma_f32_16x16x32_f16 v[50:53], v[158:161], v[144:147], v[50:53]
	ds_read_b128 v[120:123], v16 offset:32768
	ds_read_b128 v[136:139], v21
	s_waitcnt lgkmcnt(0)
	v_mfma_f32_16x16x32_f16 v[38:41], v[120:123], v[136:139], v[38:41]
	ds_read_b128 v[124:127], v16 offset:34816
	ds_read_b128 v[144:147], v21 offset:2048
	s_waitcnt lgkmcnt(0)
	v_mfma_f32_16x16x32_f16 v[80:83], v[120:123], v[144:147], v[80:83]
	ds_read_b128 v[154:157], v16 offset:36864
	v_mfma_f32_16x16x32_f16 v[46:49], v[124:127], v[136:139], v[46:49]
	ds_read_b128 v[158:161], v16 offset:38912
	v_mfma_f32_16x16x32_f16 v[104:107], v[124:127], v[144:147], v[104:107]
	s_waitcnt vmcnt(7)
	ds_write_b128 v17, v[54:57] offset:16384
	s_waitcnt lgkmcnt(2)
	v_mfma_f32_16x16x32_f16 v[108:111], v[154:157], v[136:139], v[108:111]
	s_waitcnt vmcnt(6)
	ds_write_b128 v18, v[116:119] offset:16384
	v_mfma_f32_16x16x32_f16 v[112:115], v[154:157], v[144:147], v[112:115]
	s_waitcnt vmcnt(5)
	ds_write_b128 v19, v[162:165] offset:16384
	s_waitcnt lgkmcnt(3)
	v_mfma_f32_16x16x32_f16 v[72:75], v[158:161], v[136:139], v[72:75]
	ds_read_b128 v[136:139], v21 offset:4096
	v_mfma_f32_16x16x32_f16 v[34:37], v[158:161], v[144:147], v[34:37]
	ds_read_b128 v[144:147], v21 offset:6144
	s_waitcnt lgkmcnt(1)
	v_mfma_f32_16x16x32_f16 v[128:131], v[120:123], v[136:139], v[128:131]
	s_waitcnt vmcnt(4)
	ds_write_b128 v20, v[166:169] offset:16384
	s_waitcnt lgkmcnt(1)
	v_mfma_f32_16x16x32_f16 v[42:45], v[120:123], v[144:147], v[42:45]
	ds_read_b128 v[120:123], v22 offset:32768
	v_mfma_f32_16x16x32_f16 v[132:135], v[124:127], v[136:139], v[132:135]
	s_waitcnt vmcnt(3)
	ds_write_b128 v17, v[58:61] offset:49152
	v_mfma_f32_16x16x32_f16 v[24:27], v[124:127], v[144:147], v[24:27]
	ds_read_b128 v[124:127], v22 offset:34816
	v_mfma_f32_16x16x32_f16 v[140:143], v[154:157], v[136:139], v[140:143]
	s_waitcnt vmcnt(2)
	ds_write_b128 v18, v[188:191] offset:49152
	v_mfma_f32_16x16x32_f16 v[28:31], v[154:157], v[144:147], v[28:31]
	ds_read_b128 v[154:157], v22 offset:36864
	v_mfma_f32_16x16x32_f16 v[76:79], v[158:161], v[136:139], v[76:79]
	ds_read_b128 v[136:139], v32
	v_mfma_f32_16x16x32_f16 v[50:53], v[158:161], v[144:147], v[50:53]
	ds_read_b128 v[144:147], v32 offset:2048
	s_waitcnt lgkmcnt(1)
	v_mfma_f32_16x16x32_f16 v[38:41], v[120:123], v[136:139], v[38:41]
	ds_read_b128 v[158:161], v22 offset:38912
	s_waitcnt lgkmcnt(1)
	v_mfma_f32_16x16x32_f16 v[80:83], v[120:123], v[144:147], v[80:83]
	s_waitcnt vmcnt(1)
	ds_write_b128 v19, v[192:195] offset:49152
	v_mfma_f32_16x16x32_f16 v[46:49], v[124:127], v[136:139], v[46:49]
	s_waitcnt vmcnt(0)
	ds_write_b128 v20, v[196:199] offset:49152
	v_mfma_f32_16x16x32_f16 v[104:107], v[124:127], v[144:147], v[104:107]
	v_mfma_f32_16x16x32_f16 v[108:111], v[154:157], v[136:139], v[108:111]
	v_mfma_f32_16x16x32_f16 v[112:115], v[154:157], v[144:147], v[112:115]
	s_waitcnt lgkmcnt(2)
	v_mfma_f32_16x16x32_f16 v[72:75], v[158:161], v[136:139], v[72:75]
	ds_read_b128 v[136:139], v32 offset:4096
	v_mfma_f32_16x16x32_f16 v[34:37], v[158:161], v[144:147], v[34:37]
	ds_read_b128 v[144:147], v32 offset:6144
	s_waitcnt lgkmcnt(1)
	v_mfma_f32_16x16x32_f16 v[128:131], v[120:123], v[136:139], v[128:131]
	s_waitcnt lgkmcnt(0)
	v_mfma_f32_16x16x32_f16 v[42:45], v[120:123], v[144:147], v[42:45]
	global_load_dwordx4 v[120:123], v[0:1], off offset:1536
	v_mfma_f32_16x16x32_f16 v[132:135], v[124:127], v[136:139], v[132:135]
	v_mfma_f32_16x16x32_f16 v[24:27], v[124:127], v[144:147], v[24:27]
	v_mfma_f32_16x16x32_f16 v[140:143], v[154:157], v[136:139], v[140:143]
	v_mfma_f32_16x16x32_f16 v[28:31], v[154:157], v[144:147], v[28:31]
	v_mfma_f32_16x16x32_f16 v[76:79], v[158:161], v[136:139], v[76:79]
	global_load_dwordx4 v[136:139], v[2:3], off offset:1536
	global_load_dwordx4 v[200:203], v[4:5], off offset:1536
	global_load_dwordx4 v[204:207], v[6:7], off offset:1536
	global_load_dwordx4 v[124:127], v[8:9], off offset:1536
	global_load_dwordx4 v[208:211], v[10:11], off offset:1536
	global_load_dwordx4 v[212:215], v[12:13], off offset:1536
	global_load_dwordx4 v[220:223], v[14:15], off offset:1536
	s_waitcnt lgkmcnt(0)
	s_barrier
; #define GL_LOAD(s_, kt_) if (VAR != 1) { a##s_##0 = GL_A(0, kt_); a##s_##1 = GL_A(1, kt_); a##s_##2 = GL_A(2, kt_); a##s_##3 = GL_A(3, kt_); b##s_##0 = GL_B(0, kt_); b##s_##1 = GL_B(1, kt_); b##s_##2 = GL_B(2, kt_); b##s_##3 = GL_B(3, kt_); }
; #define LDS_STORE(s_, buf_) if (VAR != 2) { LDS_ST1(sA, 0, buf_, a##s_##0) LDS_ST1(sA, 1, buf_, a##s_##1) LDS_ST1(sA, 2, buf_, a##s_##2) LDS_ST1(sA, 3, buf_, a##s_##3) LDS_ST1(sB, 0, buf_, b##s_##0) LDS_ST1(sB, 1, buf_, b##s_##1) LDS_ST1(sB, 2, buf_, b##s_##2) LDS_ST1(sB, 3, buf_, b##s_##3) }
;     ...
;   GL_LOAD(0, 0)
;   GL_LOAD(1, 1)
;   LDS_STORE(0, 0)
;   if (VAR != 4) __syncthreads();
; #pragma unroll
;   for (int kt = 0; kt < nk; kt += 2) {
;     if (kt + 2 < nk) { GL_LOAD(0, kt + 2) }
;     MMA_TILE(0)
;     LDS_STORE(1, 1)
;     if (VAR != 4) __syncthreads();
;     if (kt + 3 < nk) { GL_LOAD(1, kt + 3) }
;     MMA_TILE(1)
;     if (kt + 2 < nk) { LDS_STORE(0, 0) }
;     if (VAR != 4) __syncthreads();
	v_mfma_f32_16x16x32_f16 v[50:53], v[158:161], v[144:147], v[50:53]
	ds_read_b128 v[54:57], v16 offset:49152
	ds_read_b128 v[116:119], v21 offset:16384
	s_waitcnt lgkmcnt(0)
	v_mfma_f32_16x16x32_f16 v[38:41], v[54:57], v[116:119], v[38:41]
	ds_read_b128 v[58:61], v16 offset:51200
	ds_read_b128 v[144:147], v21 offset:18432
	s_waitcnt lgkmcnt(0)
	v_mfma_f32_16x16x32_f16 v[80:83], v[54:57], v[144:147], v[80:83]
	ds_read_b128 v[154:157], v16 offset:53248
	v_mfma_f32_16x16x32_f16 v[46:49], v[58:61], v[116:119], v[46:49]
	ds_read_b128 v[158:161], v16 offset:55296
	v_mfma_f32_16x16x32_f16 v[104:107], v[58:61], v[144:147], v[104:107]
	s_waitcnt vmcnt(7)
	ds_write_b128 v17, v[120:123]
	s_waitcnt lgkmcnt(2)
	v_mfma_f32_16x16x32_f16 v[108:111], v[154:157], v[116:119], v[108:111]
	s_waitcnt vmcnt(6)
	ds_write_b128 v18, v[136:139]
	v_mfma_f32_16x16x32_f16 v[112:115], v[154:157], v[144:147], v[112:115]
	s_waitcnt vmcnt(5)
	ds_write_b128 v19, v[200:203]
	s_waitcnt lgkmcnt(3)
	v_mfma_f32_16x16x32_f16 v[72:75], v[158:161], v[116:119], v[72:75]
	ds_read_b128 v[116:119], v21 offset:20480
	v_mfma_f32_16x16x32_f16 v[34:37], v[158:161], v[144:147], v[34:37]
	ds_read_b128 v[144:147], v21 offset:22528
	s_waitcnt lgkmcnt(1)
	v_mfma_f32_16x16x32_f16 v[128:131], v[54:57], v[116:119], v[128:131]
	s_waitcnt vmcnt(4)
	ds_write_b128 v20, v[204:207]
	s_waitcnt lgkmcnt(1)
	v_mfma_f32_16x16x32_f16 v[42:45], v[54:57], v[144:147], v[42:45]
	ds_read_b128 v[54:57], v22 offset:49152
	v_mfma_f32_16x16x32_f16 v[132:135], v[58:61], v[116:119], v[132:135]
	s_waitcnt vmcnt(3)
	ds_write_b128 v17, v[124:127] offset:32768
	v_mfma_f32_16x16x32_f16 v[24:27], v[58:61], v[144:147], v[24:27]
	ds_read_b128 v[58:61], v22 offset:51200
	v_mfma_f32_16x16x32_f16 v[140:143], v[154:157], v[116:119], v[140:143]
	s_waitcnt vmcnt(2)
	ds_write_b128 v18, v[208:211] offset:32768
	v_mfma_f32_16x16x32_f16 v[28:31], v[154:157], v[144:147], v[28:31]
	ds_read_b128 v[154:157], v22 offset:53248
	v_mfma_f32_16x16x32_f16 v[76:79], v[158:161], v[116:119], v[76:79]
	ds_read_b128 v[116:119], v32 offset:16384
	v_mfma_f32_16x16x32_f16 v[50:53], v[158:161], v[144:147], v[50:53]
	ds_read_b128 v[144:147], v32 offset:18432
	s_waitcnt lgkmcnt(1)
	v_mfma_f32_16x16x32_f16 v[38:41], v[54:57], v[116:119], v[38:41]
	ds_read_b128 v[158:161], v22 offset:55296
	s_waitcnt lgkmcnt(1)
	v_mfma_f32_16x16x32_f16 v[80:83], v[54:57], v[144:147], v[80:83]
	s_waitcnt vmcnt(1)
	ds_write_b128 v19, v[212:215] offset:32768
	v_mfma_f32_16x16x32_f16 v[46:49], v[58:61], v[116:119], v[46:49]
	s_waitcnt vmcnt(0)
	ds_write_b128 v20, v[220:223] offset:32768
	v_mfma_f32_16x16x32_f16 v[104:107], v[58:61], v[144:147], v[104:107]
	v_mfma_f32_16x16x32_f16 v[108:111], v[154:157], v[116:119], v[108:111]
	v_mfma_f32_16x16x32_f16 v[112:115], v[154:157], v[144:147], v[112:115]
	s_waitcnt lgkmcnt(2)
	v_mfma_f32_16x16x32_f16 v[72:75], v[158:161], v[116:119], v[72:75]
	ds_read_b128 v[116:119], v32 offset:20480
	v_mfma_f32_16x16x32_f16 v[34:37], v[158:161], v[144:147], v[34:37]
	ds_read_b128 v[144:147], v32 offset:22528
	s_waitcnt lgkmcnt(1)
	v_mfma_f32_16x16x32_f16 v[128:131], v[54:57], v[116:119], v[128:131]
	s_waitcnt lgkmcnt(0)
	v_mfma_f32_16x16x32_f16 v[42:45], v[54:57], v[144:147], v[42:45]
	global_load_dwordx4 v[54:57], v[0:1], off offset:1664
	v_mfma_f32_16x16x32_f16 v[132:135], v[58:61], v[116:119], v[132:135]
	v_mfma_f32_16x16x32_f16 v[24:27], v[58:61], v[144:147], v[24:27]
	v_mfma_f32_16x16x32_f16 v[140:143], v[154:157], v[116:119], v[140:143]
	v_mfma_f32_16x16x32_f16 v[28:31], v[154:157], v[144:147], v[28:31]
	v_mfma_f32_16x16x32_f16 v[76:79], v[158:161], v[116:119], v[76:79]
	global_load_dwordx4 v[116:119], v[2:3], off offset:1664
	global_load_dwordx4 v[162:165], v[4:5], off offset:1664
	global_load_dwordx4 v[166:169], v[6:7], off offset:1664
	global_load_dwordx4 v[58:61], v[8:9], off offset:1664
	global_load_dwordx4 v[188:191], v[10:11], off offset:1664
	global_load_dwordx4 v[192:195], v[12:13], off offset:1664
	global_load_dwordx4 v[196:199], v[14:15], off offset:1664
	s_waitcnt lgkmcnt(0)
	s_barrier
	v_mfma_f32_16x16x32_f16 v[50:53], v[158:161], v[144:147], v[50:53]
	ds_read_b128 v[120:123], v16 offset:32768
	ds_read_b128 v[136:139], v21
	s_waitcnt lgkmcnt(0)
	v_mfma_f32_16x16x32_f16 v[38:41], v[120:123], v[136:139], v[38:41]
	ds_read_b128 v[124:127], v16 offset:34816
	ds_read_b128 v[144:147], v21 offset:2048
	s_waitcnt lgkmcnt(0)
	v_mfma_f32_16x16x32_f16 v[80:83], v[120:123], v[144:147], v[80:83]
	ds_read_b128 v[154:157], v16 offset:36864
	v_mfma_f32_16x16x32_f16 v[46:49], v[124:127], v[136:139], v[46:49]
	ds_read_b128 v[158:161], v16 offset:38912
	v_mfma_f32_16x16x32_f16 v[104:107], v[124:127], v[144:147], v[104:107]
	s_waitcnt vmcnt(7)
	ds_write_b128 v17, v[54:57] offset:16384
	s_waitcnt lgkmcnt(2)
	v_mfma_f32_16x16x32_f16 v[108:111], v[154:157], v[136:139], v[108:111]
	s_waitcnt vmcnt(6)
	ds_write_b128 v18, v[116:119] offset:16384
	v_mfma_f32_16x16x32_f16 v[112:115], v[154:157], v[144:147], v[112:115]
	s_waitcnt vmcnt(5)
	ds_write_b128 v19, v[162:165] offset:16384
	s_waitcnt lgkmcnt(3)
	v_mfma_f32_16x16x32_f16 v[72:75], v[158:161], v[136:139], v[72:75]
	ds_read_b128 v[136:139], v21 offset:4096
	v_mfma_f32_16x16x32_f16 v[34:37], v[158:161], v[144:147], v[34:37]
	ds_read_b128 v[144:147], v21 offset:6144
	s_waitcnt lgkmcnt(1)
	v_mfma_f32_16x16x32_f16 v[128:131], v[120:123], v[136:139], v[128:131]
	s_waitcnt vmcnt(4)
	ds_write_b128 v20, v[166:169] offset:16384
	s_waitcnt lgkmcnt(1)
	v_mfma_f32_16x16x32_f16 v[42:45], v[120:123], v[144:147], v[42:45]
	ds_read_b128 v[120:123], v22 offset:32768
	v_mfma_f32_16x16x32_f16 v[132:135], v[124:127], v[136:139], v[132:135]
	s_waitcnt vmcnt(3)
; #define GL_LOAD(s_, kt_) if (VAR != 1) { a##s_##0 = GL_A(0, kt_); a##s_##1 = GL_A(1, kt_); a##s_##2 = GL_A(2, kt_); a##s_##3 = GL_A(3, kt_); b##s_##0 = GL_B(0, kt_); b##s_##1 = GL_B(1, kt_); b##s_##2 = GL_B(2, kt_); b##s_##3 = GL_B(3, kt_); }
; #define LDS_STORE(s_, buf_) if (VAR != 2) { LDS_ST1(sA, 0, buf_, a##s_##0) LDS_ST1(sA, 1, buf_, a##s_##1) LDS_ST1(sA, 2, buf_, a##s_##2) LDS_ST1(sA, 3, buf_, a##s_##3) LDS_ST1(sB, 0, buf_, b##s_##0) LDS_ST1(sB, 1, buf_, b##s_##1) LDS_ST1(sB, 2, buf_, b##s_##2) LDS_ST1(sB, 3, buf_, b##s_##3) }
;     ...
;   GL_LOAD(0, 0)
;   GL_LOAD(1, 1)
;   LDS_STORE(0, 0)
;   if (VAR != 4) __syncthreads();
; #pragma unroll
;   for (int kt = 0; kt < nk; kt += 2) {
;     if (kt + 2 < nk) { GL_LOAD(0, kt + 2) }
;     MMA_TILE(0)
;     LDS_STORE(1, 1)
;     if (VAR != 4) __syncthreads();
;     if (kt + 3 < nk) { GL_LOAD(1, kt + 3) }
;     MMA_TILE(1)
;     if (kt + 2 < nk) { LDS_STORE(0, 0) }
;     if (VAR != 4) __syncthreads();
	ds_write_b128 v17, v[58:61] offset:49152
	v_mfma_f32_16x16x32_f16 v[24:27], v[124:127], v[144:147], v[24:27]
	ds_read_b128 v[124:127], v22 offset:34816
	v_mfma_f32_16x16x32_f16 v[140:143], v[154:157], v[136:139], v[140:143]
	s_waitcnt vmcnt(2)
	ds_write_b128 v18, v[188:191] offset:49152
	v_mfma_f32_16x16x32_f16 v[28:31], v[154:157], v[144:147], v[28:31]
	ds_read_b128 v[154:157], v22 offset:36864
	v_mfma_f32_16x16x32_f16 v[76:79], v[158:161], v[136:139], v[76:79]
	ds_read_b128 v[136:139], v32
	v_mfma_f32_16x16x32_f16 v[50:53], v[158:161], v[144:147], v[50:53]
	ds_read_b128 v[144:147], v32 offset:2048
	s_waitcnt lgkmcnt(1)
	v_mfma_f32_16x16x32_f16 v[38:41], v[120:123], v[136:139], v[38:41]
	ds_read_b128 v[158:161], v22 offset:38912
	s_waitcnt lgkmcnt(1)
	v_mfma_f32_16x16x32_f16 v[80:83], v[120:123], v[144:147], v[80:83]
	s_waitcnt vmcnt(1)
	ds_write_b128 v19, v[192:195] offset:49152
	v_mfma_f32_16x16x32_f16 v[46:49], v[124:127], v[136:139], v[46:49]
	s_waitcnt vmcnt(0)
	ds_write_b128 v20, v[196:199] offset:49152
	v_mfma_f32_16x16x32_f16 v[104:107], v[124:127], v[144:147], v[104:107]
	v_mfma_f32_16x16x32_f16 v[108:111], v[154:157], v[136:139], v[108:111]
	v_mfma_f32_16x16x32_f16 v[112:115], v[154:157], v[144:147], v[112:115]
	s_waitcnt lgkmcnt(2)
	v_mfma_f32_16x16x32_f16 v[72:75], v[158:161], v[136:139], v[72:75]
	ds_read_b128 v[136:139], v32 offset:4096
	v_mfma_f32_16x16x32_f16 v[34:37], v[158:161], v[144:147], v[34:37]
	ds_read_b128 v[144:147], v32 offset:6144
	s_waitcnt lgkmcnt(1)
	v_mfma_f32_16x16x32_f16 v[128:131], v[120:123], v[136:139], v[128:131]
	s_waitcnt lgkmcnt(0)
	v_mfma_f32_16x16x32_f16 v[42:45], v[120:123], v[144:147], v[42:45]
	global_load_dwordx4 v[120:123], v[0:1], off offset:1792
	v_mfma_f32_16x16x32_f16 v[132:135], v[124:127], v[136:139], v[132:135]
	v_mfma_f32_16x16x32_f16 v[24:27], v[124:127], v[144:147], v[24:27]
	v_mfma_f32_16x16x32_f16 v[140:143], v[154:157], v[136:139], v[140:143]
	v_mfma_f32_16x16x32_f16 v[28:31], v[154:157], v[144:147], v[28:31]
	v_mfma_f32_16x16x32_f16 v[76:79], v[158:161], v[136:139], v[76:79]
	global_load_dwordx4 v[136:139], v[2:3], off offset:1792
	global_load_dwordx4 v[200:203], v[4:5], off offset:1792
	global_load_dwordx4 v[204:207], v[6:7], off offset:1792
	global_load_dwordx4 v[124:127], v[8:9], off offset:1792
	global_load_dwordx4 v[208:211], v[10:11], off offset:1792
	global_load_dwordx4 v[212:215], v[12:13], off offset:1792
	global_load_dwordx4 v[220:223], v[14:15], off offset:1792
	s_waitcnt lgkmcnt(0)
	s_barrier
	v_mfma_f32_16x16x32_f16 v[50:53], v[158:161], v[144:147], v[50:53]
	ds_read_b128 v[54:57], v16 offset:49152
	ds_read_b128 v[116:119], v21 offset:16384
	s_waitcnt lgkmcnt(0)
	v_mfma_f32_16x16x32_f16 v[38:41], v[54:57], v[116:119], v[38:41]
	ds_read_b128 v[58:61], v16 offset:51200
	ds_read_b128 v[144:147], v21 offset:18432
	s_waitcnt lgkmcnt(0)
	v_mfma_f32_16x16x32_f16 v[80:83], v[54:57], v[144:147], v[80:83]
	ds_read_b128 v[154:157], v16 offset:53248
	v_mfma_f32_16x16x32_f16 v[46:49], v[58:61], v[116:119], v[46:49]
	ds_read_b128 v[158:161], v16 offset:55296
	v_mfma_f32_16x16x32_f16 v[104:107], v[58:61], v[144:147], v[104:107]
	s_waitcnt vmcnt(7)
	ds_write_b128 v17, v[120:123]
	s_waitcnt lgkmcnt(2)
	v_mfma_f32_16x16x32_f16 v[108:111], v[154:157], v[116:119], v[108:111]
	s_waitcnt vmcnt(6)
	ds_write_b128 v18, v[136:139]
	v_mfma_f32_16x16x32_f16 v[112:115], v[154:157], v[144:147], v[112:115]
	s_waitcnt vmcnt(5)
	ds_write_b128 v19, v[200:203]
	s_waitcnt lgkmcnt(3)
	v_mfma_f32_16x16x32_f16 v[72:75], v[158:161], v[116:119], v[72:75]
	ds_read_b128 v[116:119], v21 offset:20480
	v_mfma_f32_16x16x32_f16 v[34:37], v[158:161], v[144:147], v[34:37]
	ds_read_b128 v[144:147], v21 offset:22528
	s_waitcnt lgkmcnt(1)
	v_mfma_f32_16x16x32_f16 v[128:131], v[54:57], v[116:119], v[128:131]
	s_waitcnt vmcnt(4)
	ds_write_b128 v20, v[204:207]
	s_waitcnt lgkmcnt(1)
	v_mfma_f32_16x16x32_f16 v[42:45], v[54:57], v[144:147], v[42:45]
	ds_read_b128 v[54:57], v22 offset:49152
	v_mfma_f32_16x16x32_f16 v[132:135], v[58:61], v[116:119], v[132:135]
	s_waitcnt vmcnt(3)
	ds_write_b128 v17, v[124:127] offset:32768
	v_mfma_f32_16x16x32_f16 v[24:27], v[58:61], v[144:147], v[24:27]
	ds_read_b128 v[58:61], v22 offset:51200
	v_mfma_f32_16x16x32_f16 v[140:143], v[154:157], v[116:119], v[140:143]
	s_waitcnt vmcnt(2)
	ds_write_b128 v18, v[208:211] offset:32768
	v_mfma_f32_16x16x32_f16 v[28:31], v[154:157], v[144:147], v[28:31]
	ds_read_b128 v[154:157], v22 offset:53248
	v_mfma_f32_16x16x32_f16 v[76:79], v[158:161], v[116:119], v[76:79]
	ds_read_b128 v[116:119], v32 offset:16384
	v_mfma_f32_16x16x32_f16 v[50:53], v[158:161], v[144:147], v[50:53]
	ds_read_b128 v[144:147], v32 offset:18432
	s_waitcnt lgkmcnt(1)
	v_mfma_f32_16x16x32_f16 v[38:41], v[54:57], v[116:119], v[38:41]
	ds_read_b128 v[158:161], v22 offset:55296
	s_waitcnt lgkmcnt(1)
	v_mfma_f32_16x16x32_f16 v[80:83], v[54:57], v[144:147], v[80:83]
	s_waitcnt vmcnt(1)
	ds_write_b128 v19, v[212:215] offset:32768
	v_mfma_f32_16x16x32_f16 v[46:49], v[58:61], v[116:119], v[46:49]
	s_waitcnt vmcnt(0)
	ds_write_b128 v20, v[220:223] offset:32768
	v_mfma_f32_16x16x32_f16 v[104:107], v[58:61], v[144:147], v[104:107]
	v_mfma_f32_16x16x32_f16 v[108:111], v[154:157], v[116:119], v[108:111]
	v_mfma_f32_16x16x32_f16 v[112:115], v[154:157], v[144:147], v[112:115]
	s_waitcnt lgkmcnt(2)
	v_mfma_f32_16x16x32_f16 v[72:75], v[158:161], v[116:119], v[72:75]
	ds_read_b128 v[116:119], v32 offset:20480
	v_mfma_f32_16x16x32_f16 v[34:37], v[158:161], v[144:147], v[34:37]
	ds_read_b128 v[144:147], v32 offset:22528
	s_waitcnt lgkmcnt(1)
	v_mfma_f32_16x16x32_f16 v[128:131], v[54:57], v[116:119], v[128:131]
	s_waitcnt lgkmcnt(0)
	v_mfma_f32_16x16x32_f16 v[42:45], v[54:57], v[144:147], v[42:45]
	global_load_dwordx4 v[54:57], v[0:1], off offset:1920
	global_load_dwordx4 v[0:3], v[2:3], off offset:1920
	v_mfma_f32_16x16x32_f16 v[132:135], v[58:61], v[116:119], v[132:135]
	v_mfma_f32_16x16x32_f16 v[24:27], v[58:61], v[144:147], v[24:27]
	v_mfma_f32_16x16x32_f16 v[140:143], v[154:157], v[116:119], v[140:143]
	v_mfma_f32_16x16x32_f16 v[28:31], v[154:157], v[144:147], v[28:31]
	v_mfma_f32_16x16x32_f16 v[76:79], v[158:161], v[116:119], v[76:79]
	global_load_dwordx4 v[116:119], v[4:5], off offset:1920
	global_load_dwordx4 v[4:7], v[6:7], off offset:1920
	global_load_dwordx4 v[58:61], v[8:9], off offset:1920
	global_load_dwordx4 v[8:11], v[10:11], off offset:1920
	global_load_dwordx4 v[162:165], v[12:13], off offset:1920
	global_load_dwordx4 v[12:15], v[14:15], off offset:1920
	s_waitcnt lgkmcnt(0)
	s_barrier
; #define GL_LOAD(s_, kt_) if (VAR != 1) { a##s_##0 = GL_A(0, kt_); a##s_##1 = GL_A(1, kt_); a##s_##2 = GL_A(2, kt_); a##s_##3 = GL_A(3, kt_); b##s_##0 = GL_B(0, kt_); b##s_##1 = GL_B(1, kt_); b##s_##2 = GL_B(2, kt_); b##s_##3 = GL_B(3, kt_); }
; #define LDS_STORE(s_, buf_) if (VAR != 2) { LDS_ST1(sA, 0, buf_, a##s_##0) LDS_ST1(sA, 1, buf_, a##s_##1) LDS_ST1(sA, 2, buf_, a##s_##2) LDS_ST1(sA, 3, buf_, a##s_##3) LDS_ST1(sB, 0, buf_, b##s_##0) LDS_ST1(sB, 1, buf_, b##s_##1) LDS_ST1(sB, 2, buf_, b##s_##2) LDS_ST1(sB, 3, buf_, b##s_##3) }
;     ...
;   GL_LOAD(0, 0)
;   GL_LOAD(1, 1)
;   LDS_STORE(0, 0)
;   if (VAR != 4) __syncthreads();
; #pragma unroll
;   for (int kt = 0; kt < nk; kt += 2) {
;     if (kt + 2 < nk) { GL_LOAD(0, kt + 2) }
;     MMA_TILE(0)
;     LDS_STORE(1, 1)
;     if (VAR != 4) __syncthreads();
;     if (kt + 3 < nk) { GL_LOAD(1, kt + 3) }
;     MMA_TILE(1)
;     if (kt + 2 < nk) { LDS_STORE(0, 0) }
;     if (VAR != 4) __syncthreads();
	ds_read_b128 v[120:123], v16 offset:32768
	v_mfma_f32_16x16x32_f16 v[50:53], v[158:161], v[144:147], v[50:53]
	ds_read_b128 v[124:127], v16 offset:34816
	ds_read_b128 v[136:139], v21
	ds_read_b128 v[144:147], v21 offset:2048
	ds_read_b128 v[154:157], v16 offset:36864
	ds_read_b128 v[158:161], v16 offset:38912
	s_waitcnt lgkmcnt(3)
	v_mfma_f32_16x16x32_f16 v[38:41], v[120:123], v[136:139], v[38:41]
	v_mfma_f32_16x16x32_f16 v[46:49], v[124:127], v[136:139], v[46:49]
	s_waitcnt lgkmcnt(1)
	v_mfma_f32_16x16x32_f16 v[108:111], v[154:157], v[136:139], v[108:111]
	s_waitcnt lgkmcnt(0)
	v_mfma_f32_16x16x32_f16 v[72:75], v[158:161], v[136:139], v[72:75]
	v_mfma_f32_16x16x32_f16 v[80:83], v[120:123], v[144:147], v[80:83]
	v_mfma_f32_16x16x32_f16 v[104:107], v[124:127], v[144:147], v[104:107]
	v_mfma_f32_16x16x32_f16 v[112:115], v[154:157], v[144:147], v[112:115]
	v_mfma_f32_16x16x32_f16 v[34:37], v[158:161], v[144:147], v[34:37]
	ds_read_b128 v[136:139], v21 offset:4096
	ds_read_b128 v[144:147], v21 offset:6144
	s_waitcnt lgkmcnt(1)
	v_mfma_f32_16x16x32_f16 v[128:131], v[120:123], v[136:139], v[128:131]
	v_mfma_f32_16x16x32_f16 v[132:135], v[124:127], v[136:139], v[132:135]
	v_mfma_f32_16x16x32_f16 v[140:143], v[154:157], v[136:139], v[140:143]
	v_mfma_f32_16x16x32_f16 v[76:79], v[158:161], v[136:139], v[76:79]
	s_waitcnt lgkmcnt(0)
	v_mfma_f32_16x16x32_f16 v[42:45], v[120:123], v[144:147], v[42:45]
	ds_read_b128 v[120:123], v22 offset:32768
	v_mfma_f32_16x16x32_f16 v[24:27], v[124:127], v[144:147], v[24:27]
	v_mfma_f32_16x16x32_f16 v[28:31], v[154:157], v[144:147], v[28:31]
	v_mfma_f32_16x16x32_f16 v[50:53], v[158:161], v[144:147], v[50:53]
	ds_read_b128 v[124:127], v22 offset:34816
	ds_read_b128 v[136:139], v32
	ds_read_b128 v[144:147], v32 offset:2048
	ds_read_b128 v[154:157], v22 offset:36864
	ds_read_b128 v[158:161], v22 offset:38912
	s_waitcnt lgkmcnt(3)
	v_mfma_f32_16x16x32_f16 v[38:41], v[120:123], v[136:139], v[38:41]
	v_mfma_f32_16x16x32_f16 v[46:49], v[124:127], v[136:139], v[46:49]
	s_waitcnt lgkmcnt(1)
	v_mfma_f32_16x16x32_f16 v[108:111], v[154:157], v[136:139], v[108:111]
	s_waitcnt lgkmcnt(0)
	v_mfma_f32_16x16x32_f16 v[72:75], v[158:161], v[136:139], v[72:75]
	v_mfma_f32_16x16x32_f16 v[80:83], v[120:123], v[144:147], v[80:83]
	v_mfma_f32_16x16x32_f16 v[104:107], v[124:127], v[144:147], v[104:107]
	v_mfma_f32_16x16x32_f16 v[112:115], v[154:157], v[144:147], v[112:115]
	v_mfma_f32_16x16x32_f16 v[34:37], v[158:161], v[144:147], v[34:37]
	ds_read_b128 v[136:139], v32 offset:4096
	ds_read_b128 v[144:147], v32 offset:6144
	s_waitcnt vmcnt(7)
	ds_write_b128 v17, v[54:57] offset:16384
	s_waitcnt vmcnt(6)
	ds_write_b128 v18, v[0:3] offset:16384
	s_waitcnt vmcnt(5)
	ds_write_b128 v19, v[116:119] offset:16384
	s_waitcnt vmcnt(4)
	ds_write_b128 v20, v[4:7] offset:16384
	s_waitcnt vmcnt(3)
	ds_write_b128 v17, v[58:61] offset:49152
	s_waitcnt vmcnt(2)
	ds_write_b128 v18, v[8:11] offset:49152
	s_waitcnt vmcnt(1)
	ds_write_b128 v19, v[162:165] offset:49152
	s_waitcnt vmcnt(0)
	ds_write_b128 v20, v[12:15] offset:49152
	s_waitcnt lgkmcnt(0)
	s_barrier
; #define GL_LOAD(s_, kt_) if (VAR != 1) { a##s_##0 = GL_A(0, kt_); a##s_##1 = GL_A(1, kt_); a##s_##2 = GL_A(2, kt_); a##s_##3 = GL_A(3, kt_); b##s_##0 = GL_B(0, kt_); b##s_##1 = GL_B(1, kt_); b##s_##2 = GL_B(2, kt_); b##s_##3 = GL_B(3, kt_); }
; #define LDS_STORE(s_, buf_) if (VAR != 2) { LDS_ST1(sA, 0, buf_, a##s_##0) LDS_ST1(sA, 1, buf_, a##s_##1) LDS_ST1(sA, 2, buf_, a##s_##2) LDS_ST1(sA, 3, buf_, a##s_##3) LDS_ST1(sB, 0, buf_, b##s_##0) LDS_ST1(sB, 1, buf_, b##s_##1) LDS_ST1(sB, 2, buf_, b##s_##2) LDS_ST1(sB, 3, buf_, b##s_##3) }
;     ...
;   GL_LOAD(0, 0)
;   GL_LOAD(1, 1)
;   LDS_STORE(0, 0)
;   if (VAR != 4) __syncthreads();
; #pragma unroll
;   for (int kt = 0; kt < nk; kt += 2) {
;     if (kt + 2 < nk) { GL_LOAD(0, kt + 2) }
;     MMA_TILE(0)
;     LDS_STORE(1, 1)
;     if (VAR != 4) __syncthreads();
;     if (kt + 3 < nk) { GL_LOAD(1, kt + 3) }
;     MMA_TILE(1)
;     if (kt + 2 < nk) { LDS_STORE(0, 0) }
;     if (VAR != 4) __syncthreads();
; DI void phase_proj(const Params& P, int l, char* smem) {
;     ...
;       const float* gain = nullptr; bool rope = false; float sc = 1.f; bool sig = false;
;       constexpr float QS = 0.125f * 1.4426950408889634f;
;       if (col0 < C_AK) { gain = P.a_q_norm + l * 64; rope = true; sc = QS; }
;       else if (col0 < C_BQ) { gain = P.a_k_norm + l * 64; rope = true; }
;       else if (col0 < C_BK) { sc = QS; }
;       else if (col0 < C_CQ) { }
;       else if (col0 < C_CK) { gain = P.c_q_norm + l * 64; rope = true; sc = QS; }
;       else if (col0 < C_IQ) { gain = P.c_k_norm + l * 64; rope = true; }
;       else if (col0 < C_IK) { rope = true; sc = 0.125f; }
;       else if (col0 < C_IW) { gain = P.idx_k_norm + l * 64; rope = true; }
;       else if (col0 < C_GL) { sc = 0.5f; }
;       else { sig = true; }
	ds_read_b128 v[0:3], v16 offset:49152
	v_mfma_f32_16x16x32_f16 v[4:7], v[158:161], v[144:147], v[50:53]
	ds_read_b128 v[8:11], v16 offset:51200
	ds_read_b128 v[12:15], v21 offset:16384
	s_nop 0
	ds_read_b128 v[50:53], v21 offset:18432
	ds_read_b128 v[54:57], v16 offset:53248
	ds_read_b128 v[16:19], v16 offset:55296
	s_waitcnt lgkmcnt(3)
	v_mfma_f32_16x16x32_f16 v[38:41], v[0:3], v[12:15], v[38:41]
	v_mfma_f32_16x16x32_f16 v[46:49], v[8:11], v[12:15], v[46:49]
	s_waitcnt lgkmcnt(1)
	v_mfma_f32_16x16x32_f16 v[58:61], v[54:57], v[12:15], v[108:111]
	s_waitcnt lgkmcnt(0)
	v_mfma_f32_16x16x32_f16 v[12:15], v[16:19], v[12:15], v[72:75]
	v_mfma_f32_16x16x32_f16 v[72:75], v[0:3], v[50:53], v[80:83]
	v_mfma_f32_16x16x32_f16 v[80:83], v[8:11], v[50:53], v[104:107]
	v_mfma_f32_16x16x32_f16 v[104:107], v[54:57], v[50:53], v[112:115]
	v_mfma_f32_16x16x32_f16 v[34:37], v[16:19], v[50:53], v[34:37]
	ds_read_b128 v[50:53], v21 offset:20480
	ds_read_b128 v[108:111], v21 offset:22528
	v_mfma_f32_16x16x32_f16 v[128:131], v[120:123], v[136:139], v[128:131]
	v_mfma_f32_16x16x32_f16 v[132:135], v[124:127], v[136:139], v[132:135]
	v_mfma_f32_16x16x32_f16 v[140:143], v[154:157], v[136:139], v[140:143]
	v_mfma_f32_16x16x32_f16 v[42:45], v[120:123], v[144:147], v[42:45]
	v_mfma_f32_16x16x32_f16 v[24:27], v[124:127], v[144:147], v[24:27]
	v_mfma_f32_16x16x32_f16 v[28:31], v[154:157], v[144:147], v[28:31]
	v_mfma_f32_16x16x32_f16 v[76:79], v[158:161], v[136:139], v[76:79]
	s_waitcnt lgkmcnt(1)
	v_mfma_f32_16x16x32_f16 v[112:115], v[0:3], v[50:53], v[128:131]
	v_mfma_f32_16x16x32_f16 v[116:119], v[8:11], v[50:53], v[132:135]
	v_mfma_f32_16x16x32_f16 v[120:123], v[54:57], v[50:53], v[140:143]
	s_nop 1
	ds_read_b128 v[132:135], v22 offset:49152
	s_waitcnt lgkmcnt(1)
	v_mfma_f32_16x16x32_f16 v[0:3], v[0:3], v[108:111], v[42:45]
	v_mfma_f32_16x16x32_f16 v[124:127], v[8:11], v[108:111], v[24:27]
	v_mfma_f32_16x16x32_f16 v[128:131], v[54:57], v[108:111], v[28:31]
	v_mfma_f32_16x16x32_f16 v[108:111], v[16:19], v[108:111], v[4:7]
	ds_read_b128 v[136:139], v22 offset:51200
	s_nop 1
	ds_read_b128 v[4:7], v32 offset:16384
	ds_read_b128 v[8:11], v32 offset:18432
	ds_read_b128 v[140:143], v22 offset:53248
	ds_read_b128 v[144:147], v22 offset:55296
	v_mfma_f32_16x16x32_f16 v[76:79], v[16:19], v[50:53], v[76:79]
	s_waitcnt lgkmcnt(3)
	v_mfma_f32_16x16x32_f16 v[28:31], v[132:135], v[4:7], v[38:41]
	v_mfma_f32_16x16x32_f16 v[24:27], v[136:139], v[4:7], v[46:49]
	s_waitcnt lgkmcnt(1)
	v_mfma_f32_16x16x32_f16 v[60:63], v[140:143], v[4:7], v[58:61]
	s_waitcnt lgkmcnt(0)
	v_mfma_f32_16x16x32_f16 v[56:59], v[144:147], v[4:7], v[12:15]
	v_mfma_f32_16x16x32_f16 v[48:51], v[144:147], v[8:11], v[34:37]
	ds_read_b128 v[4:7], v32 offset:20480
	s_nop 1
	ds_read_b128 v[32:35], v32 offset:22528
	s_waitcnt lgkmcnt(0)
	s_barrier
	s_setprio 0
	v_mfma_f32_16x16x32_f16 v[20:23], v[132:135], v[8:11], v[72:75]
	v_mfma_f32_16x16x32_f16 v[16:19], v[136:139], v[8:11], v[80:83]
	s_nop 1
	v_mov_b32_e32 v72, 0x3e38aa3b
	v_mfma_f32_16x16x32_f16 v[52:55], v[140:143], v[8:11], v[104:107]
	v_mfma_f32_16x16x32_f16 v[12:15], v[132:135], v[4:7], v[112:115]
	v_mfma_f32_16x16x32_f16 v[8:11], v[136:139], v[4:7], v[116:119]
	v_mfma_f32_16x16x32_f16 v[44:47], v[140:143], v[4:7], v[120:123]
	v_mfma_f32_16x16x32_f16 v[40:43], v[144:147], v[4:7], v[76:79]
	s_nop 1
	v_mov_b64_e32 v[122:123], s[14:15]
	v_mfma_f32_16x16x32_f16 v[4:7], v[132:135], v[32:35], v[0:3]
	v_mfma_f32_16x16x32_f16 v[0:3], v[136:139], v[32:35], v[124:127]
	v_mfma_f32_16x16x32_f16 v[36:39], v[140:143], v[32:35], v[128:131]
	v_mfma_f32_16x16x32_f16 v[32:35], v[144:147], v[32:35], v[108:111]
	s_and_saveexec_b64 s[4:5], vcc
	s_cbranch_execz .LBB0_654
	s_cmpk_lt_u32 s16, 0x400
	s_cbranch_scc1 .LBB0_649
	s_cmpk_lt_u32 s16, 0x600
	s_cbranch_scc1 .LBB0_650
	s_cmpk_lt_u32 s16, 0x800
	s_cbranch_scc1 .LBB0_651
	s_cmpk_lt_u32 s16, 0xa00
	s_cbranch_scc1 .LBB0_693
	s_cmpk_lt_u32 s16, 0xc00
	s_cbranch_scc1 .LBB0_694
	s_cmpk_lt_u32 s16, 0xd00
	s_cbranch_scc1 .LBB0_695
	s_movk_i32 s1, 0xd3f
	v_cmp_lt_u32_e32 vcc, s1, v94
	v_mov_b32_e32 v72, 1.0
	v_mov_b64_e32 v[122:123], s[6:7]
	s_and_saveexec_b64 s[24:25], vcc
	s_cmpk_gt_u32 s16, 0xd7f
	s_cselect_b64 s[20:21], -1, 0
	v_cndmask_b32_e64 v72, 0.5, 1.0, s[20:21]
	v_mov_b64_e32 v[122:123], 0
	s_xor_b64 s[22:23], exec, -1
	s_and_b64 s[20:21], s[20:21], exec
	s_or_b64 exec, exec, s[24:25]
	v_readlane_b32 s30, v252, 17
	v_readlane_b32 s31, v252, 18
	s_branch .LBB0_653
